# best stack + in-proj/up-proj/merge output tiles stored write-through (sc1)
# speedup vs baseline: 1.0150x; 1.0150x over previous
; #define TID (opq_v((int)threadIdx.x))
; template <int NI>
; DEVINL void gemm_kloop(const bf16_t* __restrict__ A, int lda, const bf16_t* __restrict__ Bt, int ldb, int K, int m0, int n0,
;                        unsigned char* lds, f32x16 (&acc)[NI][2]) {
;     const int tid = TID, lane = tid & 63, w = tid >> 6, wm = w & 3, wn = w >> 2, r = lane & 31, h = lane >> 5;
;     const int lrow = tid >> 3, cg = (tid & 7) ^ ((tid >> 4) & 7);
;     const bf16_t* ga = A + (size_t)(m0 + lrow) * lda + cg * 8;
;     const bf16_t* gb = Bt + (size_t)(n0 + lrow) * ldb + cg * 8;
;     unsigned char* da = lds + tid * 16;
;     unsigned char* db = lds + A_ST + tid * 16;
;     ...
;     const int nt = K >> 6;
;     asm volatile("s_waitcnt lgkmcnt(0)" ::: "memory");
;     __builtin_amdgcn_s_barrier();
;     GEMM_ISSUE(0, 0);
;     if (nt > 1) GEMM_ISSUE(1, 1);
;     const int sw = (r >> 1) & 7;
;     int o4[4];
; #pragma unroll
;     for (int ks = 0; ks < 4; ++ks) o4[ks] = ((ks * 2 + h) ^ sw) * 16;
;     int cur = 0;
;     auto compute = [&](int st_) {
;         const unsigned char* pa = lds + st_ * STAGE + (wm * 64 + r) * 128;
;         const unsigned char* pb = lds + st_ * STAGE + A_ST + (wn * 32 * NI + r) * 128;
;         bf16x8 af[2][2], bfr[2][NI];
; #pragma unroll
;         for (int i = 0; i < 2; ++i) af[0][i] = *(const bf16x8*)(pa + i * 32 * 128 + o4[0]);
; #pragma unroll
;         for (int i = 0; i < NI; ++i) bfr[0][i] = *(const bf16x8*)(pb + i * 32 * 128 + o4[0]);
.LBB0_45:
	s_mul_hi_i32 s1, s0, 0x78787879
	s_lshr_b32 s4, s1, 31
	s_ashr_i32 s1, s1, 8
	s_add_i32 s1, s1, s4
	s_mul_i32 s4, s1, 0xfffffde0
	s_add_i32 s4, s0, s4
	s_ashr_i32 s5, s4, 31
	s_lshr_b32 s5, s5, 29
	s_add_i32 s5, s4, s5
	s_and_b32 s6, s5, 0x1fffff8
	s_sub_i32 s6, s4, s6
	s_lshl_b32 s4, s5, 5
	v_mov_b32_e32 v4, v160
	s_and_b32 s4, s4, 0xffffff00
	s_lshl_b32 s1, s1, 10
	v_ashrrev_i32_e32 v2, 3, v4
	v_lshrrev_b32_e32 v0, 4, v4
	v_xor_b32_e32 v3, v0, v4
	v_add_u32_e32 v0, s4, v2
	v_ashrrev_i32_e32 v1, 31, v0
	s_lshl_b32 s5, s6, 7
	v_lshlrev_b64 v[0:1], 11, v[0:1]
	v_lshlrev_b32_e32 v3, 4, v3
	v_lshl_add_u32 v89, v4, 4, 0
	s_add_i32 s1, s5, s1
	v_lshl_add_u64 v[0:1], s[22:23], 0, v[0:1]
	v_and_b32_e32 v64, 0x70, v3
	v_readfirstlane_b32 s14, v89
	v_add_u32_e32 v92, 0x2000, v89
	v_lshl_add_u64 v[74:75], v[0:1], 0, v[64:65]
	v_add_u32_e32 v0, s1, v2
	s_mov_b32 m0, s14
	v_readfirstlane_b32 s13, v92
	v_add_u32_e32 v91, 0x4000, v89
	v_ashrrev_i32_e32 v1, 31, v0
	s_waitcnt lgkmcnt(0)
	s_barrier
	global_load_lds_dwordx4 v[74:75], off
	v_lshl_add_u64 v[2:3], v[74:75], 0, s[68:69]
	s_mov_b32 m0, s13
	v_readfirstlane_b32 s12, v91
	v_add_u32_e32 v90, 0x6000, v89
	v_lshlrev_b64 v[0:1], 11, v[0:1]
	v_add_u32_e32 v88, 0x8000, v89
	global_load_lds_dwordx4 v[2:3], off
	v_lshl_add_u64 v[2:3], v[74:75], 0, s[10:11]
	s_mov_b32 m0, s12
	v_readfirstlane_b32 s11, v90
	v_lshl_add_u64 v[0:1], s[30:31], 0, v[0:1]
	global_load_lds_dwordx4 v[2:3], off
	v_lshl_add_u64 v[2:3], v[74:75], 0, s[8:9]
	s_mov_b32 m0, s11
	v_readfirstlane_b32 s10, v88
	v_add_u32_e32 v87, 0xa000, v89
	global_load_lds_dwordx4 v[2:3], off
	v_lshl_add_u64 v[76:77], v[0:1], 0, v[64:65]
	s_mov_b32 m0, s10
	v_readfirstlane_b32 s9, v87
	v_add_u32_e32 v99, 0xc000, v89
	global_load_lds_dwordx4 v[76:77], off
	v_lshl_add_u64 v[0:1], v[76:77], 0, s[68:69]
	s_mov_b32 m0, s9
	v_readfirstlane_b32 s16, v99
	v_add_u32_e32 v97, 0xe000, v89
	global_load_lds_dwordx4 v[0:1], off
	v_lshl_add_u64 v[0:1], v[74:75], 0, s[92:93]
	s_mov_b32 m0, s16
	v_readfirstlane_b32 s15, v97
	v_add_u32_e32 v2, 0x10000, v89
	global_load_lds_dwordx4 v[0:1], off
	v_lshl_add_u64 v[0:1], v[74:75], 0, s[60:61]
	s_mov_b32 m0, s15
	v_readfirstlane_b32 s8, v2
	v_add_u32_e32 v2, 0x12000, v89
	global_load_lds_dwordx4 v[0:1], off
	v_lshl_add_u64 v[0:1], v[74:75], 0, s[18:19]
	s_mov_b32 m0, s8
	v_readfirstlane_b32 s7, v2
	v_add_u32_e32 v2, 0x14000, v89
	global_load_lds_dwordx4 v[0:1], off
	v_lshl_add_u64 v[0:1], v[74:75], 0, s[20:21]
	s_mov_b32 m0, s7
	v_readfirstlane_b32 s6, v2
	v_add_u32_e32 v2, 0x16000, v89
	global_load_lds_dwordx4 v[0:1], off
	v_lshl_add_u64 v[0:1], v[76:77], 0, s[92:93]
	s_mov_b32 m0, s6
	v_readfirstlane_b32 s5, v2
	global_load_lds_dwordx4 v[0:1], off
	v_lshl_add_u64 v[0:1], v[76:77], 0, s[60:61]
	s_mov_b32 m0, s5
	v_bfe_u32 v2, v4, 1, 3
	global_load_lds_dwordx4 v[0:1], off
	v_lshrrev_b32_e32 v0, 5, v4
	v_bfe_u32 v1, v4, 5, 1
	v_bitop3_b32 v3, v1, v2, 6 bitop3:0x36
	v_bitop3_b32 v0, v0, v2, 1 bitop3:0x6c
	v_lshlrev_b32_e32 v96, 4, v3
	v_bitop3_b32 v3, v1, v2, 4 bitop3:0x36
	v_bitop3_b32 v1, v1, v2, 2 bitop3:0x36
	v_lshlrev_b32_e32 v106, 4, v0
	v_lshlrev_b32_e32 v0, 7, v4
	v_add_u32_e32 v100, 0x18000, v89
	v_lshlrev_b32_e32 v105, 4, v1
	v_and_b32_e32 v1, 0xf80, v0
	v_and_b32_e32 v108, 0x6f80, v0
	v_lshlrev_b32_e32 v0, 5, v4
	v_readfirstlane_b32 s19, v100
	v_add_u32_e32 v101, 0x1a000, v89
	v_and_or_b32 v107, v0, s35, v1
	v_lshl_add_u64 v[0:1], v[74:75], 0, s[84:85]
	s_mov_b32 m0, s19
	v_readfirstlane_b32 s18, v101
	v_add_u32_e32 v102, 0x1c000, v89
	s_waitcnt vmcnt(6)
	s_barrier
	global_load_lds_dwordx4 v[0:1], off
	v_lshl_add_u64 v[0:1], v[74:75], 0, s[24:25]
	s_mov_b32 m0, s18
	v_readfirstlane_b32 s20, v102
	v_add_u32_e32 v103, 0x1e000, v89
	global_load_lds_dwordx4 v[0:1], off
	v_lshl_add_u64 v[0:1], v[74:75], 0, s[26:27]
	s_mov_b32 m0, s20
	s_mov_b64 s[24:25], 0x60100
	v_readfirstlane_b32 s21, v103
	v_add_u32_e32 v104, 0x20000, v89
	global_load_lds_dwordx4 v[0:1], off
	v_lshl_add_u64 v[0:1], v[74:75], 0, s[24:25]
	s_mov_b32 m0, s21
	v_readfirstlane_b32 s24, v104
	v_add_u32_e32 v98, 0x22000, v89
	global_load_lds_dwordx4 v[0:1], off
	v_lshl_add_u64 v[0:1], v[76:77], 0, s[84:85]
	s_mov_b64 s[26:27], 0x20100
	s_mov_b32 m0, s24
	v_readfirstlane_b32 s17, v98
	global_load_lds_dwordx4 v[0:1], off
	v_lshl_add_u64 v[0:1], v[76:77], 0, s[26:27]
	s_mov_b32 m0, s17
	v_add_u32_e32 v85, 0, v108
	v_add_u32_e32 v86, 0, v107
	global_load_lds_dwordx4 v[0:1], off
	v_add_u32_e32 v80, v85, v106
	v_add_u32_e32 v64, v86, v106
	v_lshlrev_b32_e32 v95, 4, v3
	ds_read_b128 v[4:7], v80
	ds_read_b128 v[0:3], v80 offset:4096
	ds_read_b128 v[8:11], v64 offset:32768
	ds_read_b128 v[12:15], v64 offset:36864
	s_waitcnt lgkmcnt(0)
	v_mfma_f32_32x32x16_bf16 v[48:63], v[8:11], v[4:7], 0
	v_add_u32_e32 v81, v85, v105
	v_add_u32_e32 v82, v86, v105
	ds_read_b128 v[66:69], v81
	ds_read_b128 v[70:73], v81 offset:4096
	ds_read_b128 v[110:113], v82 offset:32768
	ds_read_b128 v[114:117], v82 offset:36864
	v_add_u32_e32 v83, v85, v95
	v_add_u32_e32 v84, v86, v95
	ds_read_b128 v[118:121], v83
	ds_read_b128 v[122:125], v83 offset:4096
	v_mfma_f32_32x32x16_bf16 v[32:47], v[12:15], v[4:7], 0
	ds_read_b128 v[126:129], v84 offset:32768
	ds_read_b128 v[130:133], v84 offset:36864
	v_add_u32_e32 v85, v85, v96
	v_add_u32_e32 v86, v86, v96
	s_mov_b32 m0, s14
	s_mov_b64 s[96:97], 0x60180
	s_add_i32 s25, 0, 0x14000
	v_add_u32_e32 v109, s25, v107
	v_mfma_f32_32x32x16_bf16 v[16:31], v[8:11], v[0:3], 0
	v_add_u32_e32 v93, v109, v106
	v_add_u32_e32 v94, v109, v105
	s_mov_b64 s[62:63], 0x40200
	s_mov_b64 s[90:91], 0x60200
	s_add_i32 s25, 0, 0x18000
	v_add_u32_e32 v140, s25, v108
	v_add_u32_e32 v141, s42, v107
	v_mfma_f32_32x32x16_bf16 v[0:15], v[12:15], v[0:3], 0
	s_mov_b64 s[72:73], 0x40280
	s_mov_b64 s[50:51], 0x60280
	s_mov_b64 s[36:37], 0x20400
	s_mov_b64 s[52:53], 0x40680
	s_add_i32 s0, s0, s70
	s_mov_b64 s[26:27], 0x40100
	s_cmp_ge_i32 s0, s34
	s_waitcnt lgkmcnt(0)
	v_mfma_f32_32x32x16_bf16 v[48:63], v[110:113], v[66:69], v[48:63]
	v_mfma_f32_32x32x16_bf16 v[32:47], v[114:117], v[66:69], v[32:47]
	v_mfma_f32_32x32x16_bf16 v[0:15], v[114:117], v[70:73], v[0:15]
	v_mfma_f32_32x32x16_bf16 v[16:31], v[110:113], v[70:73], v[16:31]
	ds_read_b128 v[66:69], v85
	ds_read_b128 v[70:73], v85 offset:4096
	ds_read_b128 v[110:113], v86 offset:32768
	ds_read_b128 v[114:117], v86 offset:36864
	s_waitcnt vmcnt(6)
	s_barrier
; template <int NI>
; DEVINL void gemm_kloop(const bf16_t* __restrict__ A, int lda, const bf16_t* __restrict__ Bt, int ldb, int K, int m0, int n0,
;                        unsigned char* lds, f32x16 (&acc)[NI][2]) {
;     ...
;     const int nt = K >> 6;
;     asm volatile("s_waitcnt lgkmcnt(0)" ::: "memory");
;     __builtin_amdgcn_s_barrier();
;     GEMM_ISSUE(0, 0);
;     if (nt > 1) GEMM_ISSUE(1, 1);
;     const int sw = (r >> 1) & 7;
;     int o4[4];
; #pragma unroll
;     for (int ks = 0; ks < 4; ++ks) o4[ks] = ((ks * 2 + h) ^ sw) * 16;
;     int cur = 0;
;     auto compute = [&](int st_) {
;         const unsigned char* pa = lds + st_ * STAGE + (wm * 64 + r) * 128;
;         const unsigned char* pb = lds + st_ * STAGE + A_ST + (wn * 32 * NI + r) * 128;
;         bf16x8 af[2][2], bfr[2][NI];
; #pragma unroll
;         for (int i = 0; i < 2; ++i) af[0][i] = *(const bf16x8*)(pa + i * 32 * 128 + o4[0]);
; #pragma unroll
;         for (int i = 0; i < NI; ++i) bfr[0][i] = *(const bf16x8*)(pb + i * 32 * 128 + o4[0]);
; #pragma unroll
;         for (int ks = 0; ks < 4; ++ks) {
;             if (ks < 3) {
; #pragma unroll
;                 for (int i = 0; i < 2; ++i) af[(ks + 1) & 1][i] = *(const bf16x8*)(pa + i * 32 * 128 + o4[ks + 1]);
; #pragma unroll
;                 for (int i = 0; i < NI; ++i) bfr[(ks + 1) & 1][i] = *(const bf16x8*)(pb + i * 32 * 128 + o4[ks + 1]);
;             }
; #pragma unroll
;             for (int ni = 0; ni < NI; ++ni)
; #pragma unroll
;                 for (int mi = 0; mi < 2; ++mi) acc[ni][mi] = MFMA32(bfr[ks & 1][ni], af[ks & 1][mi], acc[ni][mi]);
;         }
;     };
;     int t = 0;
;     for (; t + 2 < nt; ++t) {
;         if (NI == 2) asm volatile("s_waitcnt vmcnt(6)" ::: "memory"); else asm volatile("s_waitcnt vmcnt(5)" ::: "memory");
;         __builtin_amdgcn_s_barrier();
;         { const int s2 = (cur >= 1) ? cur - 1 : 2; GEMM_ISSUE(s2, t + 2); }
;         compute(cur);
;         cur = (cur == 2) ? 0 : cur + 1;
;     }
;     if (nt >= 2) {
;         if (NI == 2) asm volatile("s_waitcnt vmcnt(6)" ::: "memory"); else asm volatile("s_waitcnt vmcnt(5)" ::: "memory");
;         __builtin_amdgcn_s_barrier();
;         compute(cur);
;         cur = (cur == 2) ? 0 : cur + 1;
;     }
;     asm volatile("s_waitcnt vmcnt(0)" ::: "memory");
;     __builtin_amdgcn_s_barrier();
;     compute(cur);
	v_mfma_f32_32x32x16_bf16 v[48:63], v[126:129], v[118:121], v[48:63]
	v_mfma_f32_32x32x16_bf16 v[32:47], v[130:133], v[118:121], v[32:47]
	v_mfma_f32_32x32x16_bf16 v[0:15], v[130:133], v[122:125], v[0:15]
	v_mfma_f32_32x32x16_bf16 v[16:31], v[126:129], v[122:125], v[16:31]
	s_waitcnt lgkmcnt(0)
	v_mfma_f32_32x32x16_bf16 v[48:63], v[110:113], v[66:69], v[48:63]
	v_mfma_f32_32x32x16_bf16 v[32:47], v[114:117], v[66:69], v[32:47]
	v_lshl_add_u64 v[66:67], v[74:75], 0, s[88:89]
	global_load_lds_dwordx4 v[66:67], off
	v_lshl_add_u64 v[66:67], v[74:75], 0, s[56:57]
	s_mov_b32 m0, s13
	s_mov_b64 s[56:57], 0x40180
	global_load_lds_dwordx4 v[66:67], off
	v_lshl_add_u64 v[66:67], v[74:75], 0, s[56:57]
	s_mov_b32 m0, s12
	v_mfma_f32_32x32x16_bf16 v[0:15], v[114:117], v[70:73], v[0:15]
	global_load_lds_dwordx4 v[66:67], off
	v_lshl_add_u64 v[66:67], v[74:75], 0, s[96:97]
	s_mov_b32 m0, s11
	s_mov_b64 s[56:57], 0x20180
	global_load_lds_dwordx4 v[66:67], off
	v_lshl_add_u64 v[66:67], v[76:77], 0, s[88:89]
	s_mov_b32 m0, s10
	v_mfma_f32_32x32x16_bf16 v[16:31], v[110:113], v[70:73], v[16:31]
	global_load_lds_dwordx4 v[66:67], off
	v_lshl_add_u64 v[66:67], v[76:77], 0, s[56:57]
	s_mov_b32 m0, s9
	s_mov_b64 s[96:97], 0x20200
	global_load_lds_dwordx4 v[66:67], off
	ds_read_b128 v[70:73], v80 offset:49152
	ds_read_b128 v[66:69], v80 offset:53248
	ds_read_b128 v[110:113], v93
	ds_read_b128 v[114:117], v93 offset:4096
	ds_read_b128 v[118:121], v81 offset:49152
	ds_read_b128 v[122:125], v81 offset:53248
	s_waitcnt lgkmcnt(0)
	v_mfma_f32_32x32x16_bf16 v[0:15], v[114:117], v[66:69], v[0:15]
	ds_read_b128 v[126:129], v94
	ds_read_b128 v[130:133], v94 offset:4096
	s_mov_b32 m0, s16
	v_mfma_f32_32x32x16_bf16 v[48:63], v[110:113], v[70:73], v[48:63]
	v_mfma_f32_32x32x16_bf16 v[16:31], v[110:113], v[66:69], v[16:31]
	v_add_u32_e32 v66, v109, v95
	v_add_u32_e32 v67, v109, v96
	v_mfma_f32_32x32x16_bf16 v[32:47], v[114:117], v[70:73], v[32:47]
	ds_read_b128 v[68:71], v83 offset:49152
	ds_read_b128 v[110:113], v83 offset:53248
	ds_read_b128 v[114:117], v66
	ds_read_b128 v[134:137], v66 offset:4096
	v_add_u32_e32 v72, v140, v95
	v_add_u32_e32 v73, v141, v95
	v_add_u32_e32 v95, v140, v96
	v_add_u32_e32 v96, v141, v96
	s_waitcnt lgkmcnt(0)
	v_mfma_f32_32x32x16_bf16 v[0:15], v[130:133], v[122:125], v[0:15]
	v_mfma_f32_32x32x16_bf16 v[48:63], v[126:129], v[118:121], v[48:63]
	v_mfma_f32_32x32x16_bf16 v[16:31], v[126:129], v[122:125], v[16:31]
	v_mfma_f32_32x32x16_bf16 v[32:47], v[130:133], v[118:121], v[32:47]
	ds_read_b128 v[118:121], v85 offset:49152
	ds_read_b128 v[122:125], v85 offset:53248
	ds_read_b128 v[126:129], v67
	ds_read_b128 v[130:133], v67 offset:4096
	s_waitcnt vmcnt(6)
	s_barrier
	v_mfma_f32_32x32x16_bf16 v[0:15], v[134:137], v[110:113], v[0:15]
	v_mfma_f32_32x32x16_bf16 v[48:63], v[114:117], v[68:71], v[48:63]
	v_mfma_f32_32x32x16_bf16 v[16:31], v[114:117], v[110:113], v[16:31]
	v_mfma_f32_32x32x16_bf16 v[32:47], v[134:137], v[68:71], v[32:47]
	v_lshl_add_u64 v[68:69], v[74:75], 0, s[58:59]
	global_load_lds_dwordx4 v[68:69], off
	v_lshl_add_u64 v[68:69], v[74:75], 0, s[96:97]
	s_mov_b32 m0, s15
	v_add_u32_e32 v70, v140, v105
	global_load_lds_dwordx4 v[68:69], off
	v_lshl_add_u64 v[68:69], v[74:75], 0, s[62:63]
	s_mov_b32 m0, s8
	s_waitcnt lgkmcnt(0)
	v_mfma_f32_32x32x16_bf16 v[0:15], v[130:133], v[122:125], v[0:15]
	global_load_lds_dwordx4 v[68:69], off
	v_lshl_add_u64 v[68:69], v[74:75], 0, s[90:91]
	s_mov_b32 m0, s7
	v_add_u32_e32 v71, v141, v105
	global_load_lds_dwordx4 v[68:69], off
	v_lshl_add_u64 v[68:69], v[76:77], 0, s[58:59]
	s_mov_b32 m0, s6
	v_mfma_f32_32x32x16_bf16 v[48:63], v[126:129], v[118:121], v[48:63]
	global_load_lds_dwordx4 v[68:69], off
	v_lshl_add_u64 v[68:69], v[76:77], 0, s[96:97]
	s_mov_b32 m0, s5
	s_mov_b64 s[62:63], 0x20280
	global_load_lds_dwordx4 v[68:69], off
	v_add_u32_e32 v68, v140, v106
	v_add_u32_e32 v69, v141, v106
	v_mfma_f32_32x32x16_bf16 v[16:31], v[126:129], v[122:125], v[16:31]
	ds_read_b128 v[108:111], v68
	ds_read_b128 v[112:115], v68 offset:4096
	s_mov_b32 m0, s19
	s_mov_b64 s[90:91], 0x20300
	v_mfma_f32_32x32x16_bf16 v[32:47], v[130:133], v[118:121], v[32:47]
	ds_read_b128 v[116:119], v69
	ds_read_b128 v[120:123], v69 offset:4096
	ds_read_b128 v[124:127], v70
	ds_read_b128 v[128:131], v70 offset:4096
	ds_read_b128 v[132:135], v71
	ds_read_b128 v[136:139], v71 offset:4096
	s_waitcnt lgkmcnt(0)
	v_mfma_f32_32x32x16_bf16 v[0:15], v[120:123], v[112:115], v[0:15]
	v_mfma_f32_32x32x16_bf16 v[48:63], v[116:119], v[108:111], v[48:63]
	v_mfma_f32_32x32x16_bf16 v[16:31], v[116:119], v[112:115], v[16:31]
	v_mfma_f32_32x32x16_bf16 v[32:47], v[120:123], v[108:111], v[32:47]
	ds_read_b128 v[106:109], v72
	ds_read_b128 v[110:113], v72 offset:4096
	ds_read_b128 v[114:117], v73
	ds_read_b128 v[118:121], v73 offset:4096
	v_mfma_f32_32x32x16_bf16 v[0:15], v[136:139], v[128:131], v[0:15]
	v_mfma_f32_32x32x16_bf16 v[48:63], v[132:135], v[124:127], v[48:63]
	v_mfma_f32_32x32x16_bf16 v[16:31], v[132:135], v[128:131], v[16:31]
	v_mfma_f32_32x32x16_bf16 v[32:47], v[136:139], v[124:127], v[32:47]
	ds_read_b128 v[122:125], v95
	ds_read_b128 v[126:129], v95 offset:4096
	ds_read_b128 v[130:133], v96
	ds_read_b128 v[134:137], v96 offset:4096
	s_waitcnt vmcnt(6)
	s_barrier
; template <int NI>
; DEVINL void gemm_kloop(const bf16_t* __restrict__ A, int lda, const bf16_t* __restrict__ Bt, int ldb, int K, int m0, int n0,
;                        unsigned char* lds, f32x16 (&acc)[NI][2]) {
;     ...
;     const int nt = K >> 6;
;     asm volatile("s_waitcnt lgkmcnt(0)" ::: "memory");
;     __builtin_amdgcn_s_barrier();
;     GEMM_ISSUE(0, 0);
;     if (nt > 1) GEMM_ISSUE(1, 1);
;     const int sw = (r >> 1) & 7;
;     int o4[4];
; #pragma unroll
;     for (int ks = 0; ks < 4; ++ks) o4[ks] = ((ks * 2 + h) ^ sw) * 16;
;     int cur = 0;
;     auto compute = [&](int st_) {
;         const unsigned char* pa = lds + st_ * STAGE + (wm * 64 + r) * 128;
;         const unsigned char* pb = lds + st_ * STAGE + A_ST + (wn * 32 * NI + r) * 128;
;         bf16x8 af[2][2], bfr[2][NI];
; #pragma unroll
;         for (int i = 0; i < 2; ++i) af[0][i] = *(const bf16x8*)(pa + i * 32 * 128 + o4[0]);
; #pragma unroll
;         for (int i = 0; i < NI; ++i) bfr[0][i] = *(const bf16x8*)(pb + i * 32 * 128 + o4[0]);
; #pragma unroll
;         for (int ks = 0; ks < 4; ++ks) {
;             if (ks < 3) {
; #pragma unroll
;                 for (int i = 0; i < 2; ++i) af[(ks + 1) & 1][i] = *(const bf16x8*)(pa + i * 32 * 128 + o4[ks + 1]);
; #pragma unroll
;                 for (int i = 0; i < NI; ++i) bfr[(ks + 1) & 1][i] = *(const bf16x8*)(pb + i * 32 * 128 + o4[ks + 1]);
;             }
; #pragma unroll
;             for (int ni = 0; ni < NI; ++ni)
; #pragma unroll
;                 for (int mi = 0; mi < 2; ++mi) acc[ni][mi] = MFMA32(bfr[ks & 1][ni], af[ks & 1][mi], acc[ni][mi]);
;         }
;     };
;     int t = 0;
;     for (; t + 2 < nt; ++t) {
;         if (NI == 2) asm volatile("s_waitcnt vmcnt(6)" ::: "memory"); else asm volatile("s_waitcnt vmcnt(5)" ::: "memory");
;         __builtin_amdgcn_s_barrier();
;         { const int s2 = (cur >= 1) ? cur - 1 : 2; GEMM_ISSUE(s2, t + 2); }
;         compute(cur);
;         cur = (cur == 2) ? 0 : cur + 1;
;     }
;     if (nt >= 2) {
;         if (NI == 2) asm volatile("s_waitcnt vmcnt(6)" ::: "memory"); else asm volatile("s_waitcnt vmcnt(5)" ::: "memory");
;         __builtin_amdgcn_s_barrier();
;         compute(cur);
;         cur = (cur == 2) ? 0 : cur + 1;
;     }
;     asm volatile("s_waitcnt vmcnt(0)" ::: "memory");
;     __builtin_amdgcn_s_barrier();
;     compute(cur);
	s_waitcnt lgkmcnt(0)
	v_mfma_f32_32x32x16_bf16 v[0:15], v[118:121], v[110:113], v[0:15]
	v_mfma_f32_32x32x16_bf16 v[48:63], v[114:117], v[106:109], v[48:63]
	v_mfma_f32_32x32x16_bf16 v[16:31], v[114:117], v[110:113], v[16:31]
	v_mfma_f32_32x32x16_bf16 v[32:47], v[118:121], v[106:109], v[32:47]
	v_lshl_add_u64 v[106:107], v[74:75], 0, s[64:65]
	global_load_lds_dwordx4 v[106:107], off
	v_lshl_add_u64 v[106:107], v[74:75], 0, s[62:63]
	s_mov_b32 m0, s18
	s_nop 0
	global_load_lds_dwordx4 v[106:107], off
	v_mfma_f32_32x32x16_bf16 v[0:15], v[134:137], v[126:129], v[0:15]
	v_lshl_add_u64 v[106:107], v[74:75], 0, s[72:73]
	s_mov_b32 m0, s20
	s_mov_b64 s[72:73], 0x20380
	global_load_lds_dwordx4 v[106:107], off
	v_lshl_add_u64 v[106:107], v[74:75], 0, s[50:51]
	s_mov_b32 m0, s21
	v_mfma_f32_32x32x16_bf16 v[48:63], v[130:133], v[122:125], v[48:63]
	global_load_lds_dwordx4 v[106:107], off
	v_lshl_add_u64 v[106:107], v[76:77], 0, s[64:65]
	s_mov_b32 m0, s24
	s_mov_b64 s[50:51], 0x40300
	global_load_lds_dwordx4 v[106:107], off
	v_lshl_add_u64 v[106:107], v[76:77], 0, s[62:63]
	s_mov_b32 m0, s17
	v_mfma_f32_32x32x16_bf16 v[16:31], v[130:133], v[126:129], v[16:31]
	global_load_lds_dwordx4 v[106:107], off
	s_mov_b32 m0, s14
	v_mfma_f32_32x32x16_bf16 v[32:47], v[134:137], v[122:125], v[32:47]
	ds_read_b128 v[106:109], v80
	ds_read_b128 v[110:113], v80 offset:4096
	ds_read_b128 v[114:117], v64 offset:32768
	ds_read_b128 v[118:121], v64 offset:36864
	ds_read_b128 v[122:125], v81
	ds_read_b128 v[126:129], v81 offset:4096
	ds_read_b128 v[130:133], v82 offset:32768
	ds_read_b128 v[134:137], v82 offset:36864
	s_waitcnt lgkmcnt(0)
	v_mfma_f32_32x32x16_bf16 v[0:15], v[118:121], v[110:113], v[0:15]
	v_mfma_f32_32x32x16_bf16 v[48:63], v[114:117], v[106:109], v[48:63]
	v_mfma_f32_32x32x16_bf16 v[16:31], v[114:117], v[110:113], v[16:31]
	v_mfma_f32_32x32x16_bf16 v[32:47], v[118:121], v[106:109], v[32:47]
	ds_read_b128 v[106:109], v83
	ds_read_b128 v[110:113], v83 offset:4096
	ds_read_b128 v[114:117], v84 offset:32768
	ds_read_b128 v[118:121], v84 offset:36864
	v_mfma_f32_32x32x16_bf16 v[0:15], v[134:137], v[126:129], v[0:15]
	v_mfma_f32_32x32x16_bf16 v[48:63], v[130:133], v[122:125], v[48:63]
	v_mfma_f32_32x32x16_bf16 v[16:31], v[130:133], v[126:129], v[16:31]
	v_mfma_f32_32x32x16_bf16 v[32:47], v[134:137], v[122:125], v[32:47]
	ds_read_b128 v[122:125], v85
	ds_read_b128 v[126:129], v85 offset:4096
	ds_read_b128 v[130:133], v86 offset:32768
	ds_read_b128 v[134:137], v86 offset:36864
	s_waitcnt vmcnt(6)
	s_barrier
	s_waitcnt lgkmcnt(0)
	v_mfma_f32_32x32x16_bf16 v[0:15], v[118:121], v[110:113], v[0:15]
	v_mfma_f32_32x32x16_bf16 v[48:63], v[114:117], v[106:109], v[48:63]
	v_mfma_f32_32x32x16_bf16 v[16:31], v[114:117], v[110:113], v[16:31]
	v_mfma_f32_32x32x16_bf16 v[32:47], v[118:121], v[106:109], v[32:47]
	v_lshl_add_u64 v[106:107], v[74:75], 0, s[2:3]
	global_load_lds_dwordx4 v[106:107], off
	v_lshl_add_u64 v[106:107], v[74:75], 0, s[90:91]
	s_mov_b32 m0, s13
	s_nop 0
	global_load_lds_dwordx4 v[106:107], off
	v_mfma_f32_32x32x16_bf16 v[0:15], v[134:137], v[126:129], v[0:15]
	v_lshl_add_u64 v[106:107], v[74:75], 0, s[50:51]
	s_mov_b64 s[50:51], 0x60300
	s_mov_b32 m0, s12
	s_nop 0
	global_load_lds_dwordx4 v[106:107], off
	v_lshl_add_u64 v[106:107], v[74:75], 0, s[50:51]
	s_mov_b32 m0, s11
	v_mfma_f32_32x32x16_bf16 v[48:63], v[130:133], v[122:125], v[48:63]
	global_load_lds_dwordx4 v[106:107], off
	v_lshl_add_u64 v[106:107], v[76:77], 0, s[2:3]
	s_mov_b32 m0, s10
	s_mov_b64 s[50:51], 0x40380
	global_load_lds_dwordx4 v[106:107], off
	v_lshl_add_u64 v[106:107], v[76:77], 0, s[90:91]
	s_mov_b32 m0, s9
	v_mfma_f32_32x32x16_bf16 v[16:31], v[130:133], v[126:129], v[16:31]
	global_load_lds_dwordx4 v[106:107], off
	s_mov_b32 m0, s16
	v_mfma_f32_32x32x16_bf16 v[32:47], v[134:137], v[122:125], v[32:47]
	ds_read_b128 v[106:109], v80 offset:49152
	ds_read_b128 v[110:113], v80 offset:53248
	ds_read_b128 v[114:117], v93
	ds_read_b128 v[118:121], v93 offset:4096
	ds_read_b128 v[122:125], v81 offset:49152
	ds_read_b128 v[126:129], v81 offset:53248
	ds_read_b128 v[130:133], v94
	ds_read_b128 v[134:137], v94 offset:4096
	s_waitcnt lgkmcnt(0)
	v_mfma_f32_32x32x16_bf16 v[0:15], v[118:121], v[110:113], v[0:15]
	v_mfma_f32_32x32x16_bf16 v[48:63], v[114:117], v[106:109], v[48:63]
	v_mfma_f32_32x32x16_bf16 v[16:31], v[114:117], v[110:113], v[16:31]
	v_mfma_f32_32x32x16_bf16 v[32:47], v[118:121], v[106:109], v[32:47]
	ds_read_b128 v[106:109], v83 offset:49152
	ds_read_b128 v[110:113], v83 offset:53248
	ds_read_b128 v[114:117], v66
	ds_read_b128 v[118:121], v66 offset:4096
	v_mfma_f32_32x32x16_bf16 v[0:15], v[134:137], v[126:129], v[0:15]
	v_mfma_f32_32x32x16_bf16 v[48:63], v[130:133], v[122:125], v[48:63]
	v_mfma_f32_32x32x16_bf16 v[16:31], v[130:133], v[126:129], v[16:31]
	v_mfma_f32_32x32x16_bf16 v[32:47], v[134:137], v[122:125], v[32:47]
	ds_read_b128 v[122:125], v85 offset:49152
	ds_read_b128 v[126:129], v85 offset:53248
	ds_read_b128 v[130:133], v67
	ds_read_b128 v[134:137], v67 offset:4096
	s_waitcnt vmcnt(6)
	s_barrier
; template <int NI>
; DEVINL void gemm_kloop(const bf16_t* __restrict__ A, int lda, const bf16_t* __restrict__ Bt, int ldb, int K, int m0, int n0,
;                        unsigned char* lds, f32x16 (&acc)[NI][2]) {
;     ...
;     const int nt = K >> 6;
;     asm volatile("s_waitcnt lgkmcnt(0)" ::: "memory");
;     __builtin_amdgcn_s_barrier();
;     GEMM_ISSUE(0, 0);
;     if (nt > 1) GEMM_ISSUE(1, 1);
;     const int sw = (r >> 1) & 7;
;     int o4[4];
; #pragma unroll
;     for (int ks = 0; ks < 4; ++ks) o4[ks] = ((ks * 2 + h) ^ sw) * 16;
;     int cur = 0;
;     auto compute = [&](int st_) {
;         const unsigned char* pa = lds + st_ * STAGE + (wm * 64 + r) * 128;
;         const unsigned char* pb = lds + st_ * STAGE + A_ST + (wn * 32 * NI + r) * 128;
;         bf16x8 af[2][2], bfr[2][NI];
; #pragma unroll
;         for (int i = 0; i < 2; ++i) af[0][i] = *(const bf16x8*)(pa + i * 32 * 128 + o4[0]);
; #pragma unroll
;         for (int i = 0; i < NI; ++i) bfr[0][i] = *(const bf16x8*)(pb + i * 32 * 128 + o4[0]);
; #pragma unroll
;         for (int ks = 0; ks < 4; ++ks) {
;             if (ks < 3) {
; #pragma unroll
;                 for (int i = 0; i < 2; ++i) af[(ks + 1) & 1][i] = *(const bf16x8*)(pa + i * 32 * 128 + o4[ks + 1]);
; #pragma unroll
;                 for (int i = 0; i < NI; ++i) bfr[(ks + 1) & 1][i] = *(const bf16x8*)(pb + i * 32 * 128 + o4[ks + 1]);
;             }
; #pragma unroll
;             for (int ni = 0; ni < NI; ++ni)
; #pragma unroll
;                 for (int mi = 0; mi < 2; ++mi) acc[ni][mi] = MFMA32(bfr[ks & 1][ni], af[ks & 1][mi], acc[ni][mi]);
;         }
;     };
;     int t = 0;
;     for (; t + 2 < nt; ++t) {
;         if (NI == 2) asm volatile("s_waitcnt vmcnt(6)" ::: "memory"); else asm volatile("s_waitcnt vmcnt(5)" ::: "memory");
;         __builtin_amdgcn_s_barrier();
;         { const int s2 = (cur >= 1) ? cur - 1 : 2; GEMM_ISSUE(s2, t + 2); }
;         compute(cur);
;         cur = (cur == 2) ? 0 : cur + 1;
;     }
;     if (nt >= 2) {
;         if (NI == 2) asm volatile("s_waitcnt vmcnt(6)" ::: "memory"); else asm volatile("s_waitcnt vmcnt(5)" ::: "memory");
;         __builtin_amdgcn_s_barrier();
;         compute(cur);
;         cur = (cur == 2) ? 0 : cur + 1;
;     }
;     asm volatile("s_waitcnt vmcnt(0)" ::: "memory");
;     __builtin_amdgcn_s_barrier();
;     compute(cur);
	s_waitcnt lgkmcnt(0)
	v_mfma_f32_32x32x16_bf16 v[0:15], v[118:121], v[110:113], v[0:15]
	v_mfma_f32_32x32x16_bf16 v[48:63], v[114:117], v[106:109], v[48:63]
	v_mfma_f32_32x32x16_bf16 v[16:31], v[114:117], v[110:113], v[16:31]
	v_mfma_f32_32x32x16_bf16 v[32:47], v[118:121], v[106:109], v[32:47]
	v_lshl_add_u64 v[106:107], v[74:75], 0, s[40:41]
	global_load_lds_dwordx4 v[106:107], off
	v_lshl_add_u64 v[106:107], v[74:75], 0, s[72:73]
	s_mov_b32 m0, s15
	s_nop 0
	global_load_lds_dwordx4 v[106:107], off
	v_mfma_f32_32x32x16_bf16 v[0:15], v[134:137], v[126:129], v[0:15]
	v_lshl_add_u64 v[106:107], v[74:75], 0, s[50:51]
	s_mov_b64 s[50:51], 0x60380
	s_mov_b32 m0, s8
	s_nop 0
	global_load_lds_dwordx4 v[106:107], off
	v_lshl_add_u64 v[106:107], v[74:75], 0, s[50:51]
	s_mov_b32 m0, s7
	v_mfma_f32_32x32x16_bf16 v[48:63], v[130:133], v[122:125], v[48:63]
	global_load_lds_dwordx4 v[106:107], off
	v_lshl_add_u64 v[106:107], v[76:77], 0, s[40:41]
	s_mov_b32 m0, s6
	s_mov_b64 s[50:51], 0x400
	global_load_lds_dwordx4 v[106:107], off
	v_lshl_add_u64 v[106:107], v[76:77], 0, s[72:73]
	s_mov_b32 m0, s5
	v_mfma_f32_32x32x16_bf16 v[16:31], v[130:133], v[126:129], v[16:31]
	global_load_lds_dwordx4 v[106:107], off
	s_mov_b32 m0, s19
	v_mfma_f32_32x32x16_bf16 v[32:47], v[134:137], v[122:125], v[32:47]
	ds_read_b128 v[106:109], v68
	ds_read_b128 v[110:113], v68 offset:4096
	ds_read_b128 v[114:117], v69
	ds_read_b128 v[118:121], v69 offset:4096
	ds_read_b128 v[122:125], v70
	ds_read_b128 v[126:129], v70 offset:4096
	ds_read_b128 v[130:133], v71
	ds_read_b128 v[134:137], v71 offset:4096
	s_waitcnt lgkmcnt(0)
	v_mfma_f32_32x32x16_bf16 v[0:15], v[118:121], v[110:113], v[0:15]
	v_mfma_f32_32x32x16_bf16 v[48:63], v[114:117], v[106:109], v[48:63]
	v_mfma_f32_32x32x16_bf16 v[16:31], v[114:117], v[110:113], v[16:31]
	v_mfma_f32_32x32x16_bf16 v[32:47], v[118:121], v[106:109], v[32:47]
	ds_read_b128 v[106:109], v72
	ds_read_b128 v[110:113], v72 offset:4096
	ds_read_b128 v[114:117], v73
	ds_read_b128 v[118:121], v73 offset:4096
	v_mfma_f32_32x32x16_bf16 v[0:15], v[134:137], v[126:129], v[0:15]
	v_mfma_f32_32x32x16_bf16 v[48:63], v[130:133], v[122:125], v[48:63]
	v_mfma_f32_32x32x16_bf16 v[16:31], v[130:133], v[126:129], v[16:31]
	v_mfma_f32_32x32x16_bf16 v[32:47], v[134:137], v[122:125], v[32:47]
	ds_read_b128 v[122:125], v95
	ds_read_b128 v[126:129], v95 offset:4096
	ds_read_b128 v[130:133], v96
	ds_read_b128 v[134:137], v96 offset:4096
	s_waitcnt vmcnt(6)
	s_barrier
	s_waitcnt lgkmcnt(0)
	v_mfma_f32_32x32x16_bf16 v[0:15], v[118:121], v[110:113], v[0:15]
	v_mfma_f32_32x32x16_bf16 v[48:63], v[114:117], v[106:109], v[48:63]
	v_mfma_f32_32x32x16_bf16 v[16:31], v[114:117], v[110:113], v[16:31]
	v_mfma_f32_32x32x16_bf16 v[32:47], v[118:121], v[106:109], v[32:47]
	v_lshl_add_u64 v[106:107], v[74:75], 0, s[50:51]
	global_load_lds_dwordx4 v[106:107], off
	v_lshl_add_u64 v[106:107], v[74:75], 0, s[36:37]
	s_mov_b64 s[36:37], 0x40400
	s_mov_b32 m0, s18
	s_mov_b64 s[18:19], 0x60400
	v_mfma_f32_32x32x16_bf16 v[0:15], v[134:137], v[126:129], v[0:15]
	global_load_lds_dwordx4 v[106:107], off
	v_lshl_add_u64 v[106:107], v[74:75], 0, s[36:37]
	s_mov_b32 m0, s20
	s_mov_b64 s[36:37], 0x480
	global_load_lds_dwordx4 v[106:107], off
	v_lshl_add_u64 v[106:107], v[74:75], 0, s[18:19]
	s_mov_b32 m0, s21
	s_mov_b64 s[18:19], 0x20400
	global_load_lds_dwordx4 v[106:107], off
	v_lshl_add_u64 v[106:107], v[76:77], 0, s[50:51]
	s_mov_b32 m0, s24
	v_mfma_f32_32x32x16_bf16 v[48:63], v[130:133], v[122:125], v[48:63]
	global_load_lds_dwordx4 v[106:107], off
	v_lshl_add_u64 v[106:107], v[76:77], 0, s[18:19]
	s_mov_b32 m0, s17
	s_mov_b64 s[20:21], 0x20480
	global_load_lds_dwordx4 v[106:107], off
	v_mfma_f32_32x32x16_bf16 v[16:31], v[130:133], v[126:129], v[16:31]
	s_mov_b32 m0, s14
	s_mov_b64 s[50:51], 0x40480
	s_mov_b64 s[14:15], 0x60480
	s_mov_b64 s[16:17], 0x40500
	s_mov_b64 s[18:19], 0x60500
	s_mov_b64 s[24:25], 0x580
	v_mfma_f32_32x32x16_bf16 v[32:47], v[134:137], v[122:125], v[32:47]
	ds_read_b128 v[106:109], v80
	ds_read_b128 v[110:113], v80 offset:4096
	ds_read_b128 v[114:117], v64 offset:32768
	ds_read_b128 v[118:121], v64 offset:36864
	ds_read_b128 v[122:125], v81
	ds_read_b128 v[126:129], v81 offset:4096
	ds_read_b128 v[130:133], v82 offset:32768
	ds_read_b128 v[134:137], v82 offset:36864
	s_waitcnt lgkmcnt(0)
	v_mfma_f32_32x32x16_bf16 v[0:15], v[118:121], v[110:113], v[0:15]
	v_mfma_f32_32x32x16_bf16 v[48:63], v[114:117], v[106:109], v[48:63]
	v_mfma_f32_32x32x16_bf16 v[16:31], v[114:117], v[110:113], v[16:31]
	v_mfma_f32_32x32x16_bf16 v[32:47], v[118:121], v[106:109], v[32:47]
	ds_read_b128 v[106:109], v83
	ds_read_b128 v[110:113], v83 offset:4096
	ds_read_b128 v[114:117], v84 offset:32768
	ds_read_b128 v[118:121], v84 offset:36864
	v_mfma_f32_32x32x16_bf16 v[0:15], v[134:137], v[126:129], v[0:15]
	v_mfma_f32_32x32x16_bf16 v[48:63], v[130:133], v[122:125], v[48:63]
	v_mfma_f32_32x32x16_bf16 v[16:31], v[130:133], v[126:129], v[16:31]
	v_mfma_f32_32x32x16_bf16 v[32:47], v[134:137], v[122:125], v[32:47]
	ds_read_b128 v[122:125], v85
	ds_read_b128 v[126:129], v85 offset:4096
	ds_read_b128 v[130:133], v86 offset:32768
	ds_read_b128 v[134:137], v86 offset:36864
	s_waitcnt vmcnt(6)
	s_barrier
; template <int NI>
; DEVINL void gemm_kloop(const bf16_t* __restrict__ A, int lda, const bf16_t* __restrict__ Bt, int ldb, int K, int m0, int n0,
;                        unsigned char* lds, f32x16 (&acc)[NI][2]) {
;     ...
;     const int nt = K >> 6;
;     asm volatile("s_waitcnt lgkmcnt(0)" ::: "memory");
;     __builtin_amdgcn_s_barrier();
;     GEMM_ISSUE(0, 0);
;     if (nt > 1) GEMM_ISSUE(1, 1);
;     const int sw = (r >> 1) & 7;
;     int o4[4];
; #pragma unroll
;     for (int ks = 0; ks < 4; ++ks) o4[ks] = ((ks * 2 + h) ^ sw) * 16;
;     int cur = 0;
;     auto compute = [&](int st_) {
;         const unsigned char* pa = lds + st_ * STAGE + (wm * 64 + r) * 128;
;         const unsigned char* pb = lds + st_ * STAGE + A_ST + (wn * 32 * NI + r) * 128;
;         bf16x8 af[2][2], bfr[2][NI];
; #pragma unroll
;         for (int i = 0; i < 2; ++i) af[0][i] = *(const bf16x8*)(pa + i * 32 * 128 + o4[0]);
; #pragma unroll
;         for (int i = 0; i < NI; ++i) bfr[0][i] = *(const bf16x8*)(pb + i * 32 * 128 + o4[0]);
; #pragma unroll
;         for (int ks = 0; ks < 4; ++ks) {
;             if (ks < 3) {
; #pragma unroll
;                 for (int i = 0; i < 2; ++i) af[(ks + 1) & 1][i] = *(const bf16x8*)(pa + i * 32 * 128 + o4[ks + 1]);
; #pragma unroll
;                 for (int i = 0; i < NI; ++i) bfr[(ks + 1) & 1][i] = *(const bf16x8*)(pb + i * 32 * 128 + o4[ks + 1]);
;             }
; #pragma unroll
;             for (int ni = 0; ni < NI; ++ni)
; #pragma unroll
;                 for (int mi = 0; mi < 2; ++mi) acc[ni][mi] = MFMA32(bfr[ks & 1][ni], af[ks & 1][mi], acc[ni][mi]);
;         }
;     };
;     int t = 0;
;     for (; t + 2 < nt; ++t) {
;         if (NI == 2) asm volatile("s_waitcnt vmcnt(6)" ::: "memory"); else asm volatile("s_waitcnt vmcnt(5)" ::: "memory");
;         __builtin_amdgcn_s_barrier();
;         { const int s2 = (cur >= 1) ? cur - 1 : 2; GEMM_ISSUE(s2, t + 2); }
;         compute(cur);
;         cur = (cur == 2) ? 0 : cur + 1;
;     }
;     if (nt >= 2) {
;         if (NI == 2) asm volatile("s_waitcnt vmcnt(6)" ::: "memory"); else asm volatile("s_waitcnt vmcnt(5)" ::: "memory");
;         __builtin_amdgcn_s_barrier();
;         compute(cur);
;         cur = (cur == 2) ? 0 : cur + 1;
;     }
;     asm volatile("s_waitcnt vmcnt(0)" ::: "memory");
;     __builtin_amdgcn_s_barrier();
;     compute(cur);
	s_waitcnt lgkmcnt(0)
	v_mfma_f32_32x32x16_bf16 v[0:15], v[118:121], v[110:113], v[0:15]
	v_mfma_f32_32x32x16_bf16 v[48:63], v[114:117], v[106:109], v[48:63]
	v_mfma_f32_32x32x16_bf16 v[16:31], v[114:117], v[110:113], v[16:31]
	v_mfma_f32_32x32x16_bf16 v[32:47], v[118:121], v[106:109], v[32:47]
	v_lshl_add_u64 v[106:107], v[74:75], 0, s[36:37]
	global_load_lds_dwordx4 v[106:107], off
	v_lshl_add_u64 v[106:107], v[74:75], 0, s[20:21]
	s_mov_b32 m0, s13
	s_nop 0
	global_load_lds_dwordx4 v[106:107], off
	v_mfma_f32_32x32x16_bf16 v[0:15], v[134:137], v[126:129], v[0:15]
	v_lshl_add_u64 v[106:107], v[74:75], 0, s[50:51]
	s_mov_b32 m0, s12
	s_mov_b64 s[12:13], 0x500
	global_load_lds_dwordx4 v[106:107], off
	v_lshl_add_u64 v[106:107], v[74:75], 0, s[14:15]
	s_mov_b32 m0, s11
	v_mfma_f32_32x32x16_bf16 v[48:63], v[130:133], v[122:125], v[48:63]
	global_load_lds_dwordx4 v[106:107], off
	v_lshl_add_u64 v[106:107], v[76:77], 0, s[36:37]
	s_mov_b32 m0, s10
	v_readfirstlane_b32 s10, v99
	global_load_lds_dwordx4 v[106:107], off
	v_lshl_add_u64 v[106:107], v[76:77], 0, s[20:21]
	s_mov_b32 m0, s9
	v_mfma_f32_32x32x16_bf16 v[16:31], v[130:133], v[126:129], v[16:31]
	global_load_lds_dwordx4 v[106:107], off
	s_mov_b64 s[14:15], 0x20500
	s_mov_b32 m0, s10
	v_readfirstlane_b32 s9, v97
	s_mov_b64 s[36:37], 0x20580
	v_readfirstlane_b32 s11, v101
	v_mfma_f32_32x32x16_bf16 v[32:47], v[134:137], v[122:125], v[32:47]
	ds_read_b128 v[106:109], v80 offset:49152
	ds_read_b128 v[110:113], v80 offset:53248
	ds_read_b128 v[114:117], v93
	ds_read_b128 v[118:121], v93 offset:4096
	ds_read_b128 v[122:125], v81 offset:49152
	ds_read_b128 v[126:129], v81 offset:53248
	ds_read_b128 v[130:133], v94
	ds_read_b128 v[134:137], v94 offset:4096
	s_mov_b64 s[50:51], 0x40580
	v_readfirstlane_b32 s20, v98
	v_readfirstlane_b32 s21, v89
	s_waitcnt lgkmcnt(0)
	v_mfma_f32_32x32x16_bf16 v[0:15], v[118:121], v[110:113], v[0:15]
	v_mfma_f32_32x32x16_bf16 v[48:63], v[114:117], v[106:109], v[48:63]
	v_mfma_f32_32x32x16_bf16 v[16:31], v[114:117], v[110:113], v[16:31]
	v_mfma_f32_32x32x16_bf16 v[32:47], v[118:121], v[106:109], v[32:47]
	ds_read_b128 v[106:109], v83 offset:49152
	ds_read_b128 v[110:113], v83 offset:53248
	ds_read_b128 v[114:117], v66
	ds_read_b128 v[118:121], v66 offset:4096
	v_mfma_f32_32x32x16_bf16 v[0:15], v[134:137], v[126:129], v[0:15]
	v_mfma_f32_32x32x16_bf16 v[48:63], v[130:133], v[122:125], v[48:63]
	v_mfma_f32_32x32x16_bf16 v[16:31], v[130:133], v[126:129], v[16:31]
	v_mfma_f32_32x32x16_bf16 v[32:47], v[134:137], v[122:125], v[32:47]
	ds_read_b128 v[122:125], v85 offset:49152
	ds_read_b128 v[126:129], v85 offset:53248
	ds_read_b128 v[130:133], v67
	ds_read_b128 v[134:137], v67 offset:4096
	s_waitcnt vmcnt(6)
	s_barrier
	s_waitcnt lgkmcnt(0)
	v_mfma_f32_32x32x16_bf16 v[0:15], v[118:121], v[110:113], v[0:15]
	v_mfma_f32_32x32x16_bf16 v[48:63], v[114:117], v[106:109], v[48:63]
	v_mfma_f32_32x32x16_bf16 v[16:31], v[114:117], v[110:113], v[16:31]
	v_mfma_f32_32x32x16_bf16 v[32:47], v[118:121], v[106:109], v[32:47]
	v_lshl_add_u64 v[106:107], v[74:75], 0, s[12:13]
	global_load_lds_dwordx4 v[106:107], off
	v_lshl_add_u64 v[106:107], v[74:75], 0, s[14:15]
	s_mov_b32 m0, s9
	s_nop 0
	global_load_lds_dwordx4 v[106:107], off
	v_mfma_f32_32x32x16_bf16 v[0:15], v[134:137], v[126:129], v[0:15]
	v_lshl_add_u64 v[106:107], v[74:75], 0, s[16:17]
	s_mov_b32 m0, s8
	s_mov_b64 s[16:17], 0x60580
	global_load_lds_dwordx4 v[106:107], off
	v_lshl_add_u64 v[106:107], v[74:75], 0, s[18:19]
	s_mov_b32 m0, s7
	v_mfma_f32_32x32x16_bf16 v[48:63], v[130:133], v[122:125], v[48:63]
	global_load_lds_dwordx4 v[106:107], off
	v_lshl_add_u64 v[106:107], v[76:77], 0, s[12:13]
	s_mov_b32 m0, s6
	v_readfirstlane_b32 s12, v102
	global_load_lds_dwordx4 v[106:107], off
	v_lshl_add_u64 v[106:107], v[76:77], 0, s[14:15]
	s_mov_b32 m0, s5
	v_mfma_f32_32x32x16_bf16 v[16:31], v[130:133], v[126:129], v[16:31]
	global_load_lds_dwordx4 v[106:107], off
	v_readfirstlane_b32 s15, v100
	s_mov_b32 m0, s15
	v_lshl_add_u64 v[100:101], v[74:75], 0, s[50:51]
	v_readfirstlane_b32 s13, v103
	v_readfirstlane_b32 s14, v104
	v_mfma_f32_32x32x16_bf16 v[32:47], v[134:137], v[122:125], v[32:47]
	ds_read_b128 v[106:109], v68
	ds_read_b128 v[110:113], v68 offset:4096
	ds_read_b128 v[114:117], v69
	ds_read_b128 v[118:121], v69 offset:4096
	ds_read_b128 v[122:125], v70
	ds_read_b128 v[126:129], v70 offset:4096
	ds_read_b128 v[130:133], v71
	ds_read_b128 v[134:137], v71 offset:4096
	s_mov_b64 s[18:19], 0x40600
	s_mov_b64 s[50:51], 0x60600
	s_waitcnt lgkmcnt(0)
	v_mfma_f32_32x32x16_bf16 v[0:15], v[118:121], v[110:113], v[0:15]
	v_mfma_f32_32x32x16_bf16 v[48:63], v[114:117], v[106:109], v[48:63]
	v_mfma_f32_32x32x16_bf16 v[16:31], v[114:117], v[110:113], v[16:31]
	v_mfma_f32_32x32x16_bf16 v[32:47], v[118:121], v[106:109], v[32:47]
	ds_read_b128 v[106:109], v72
	ds_read_b128 v[110:113], v72 offset:4096
	ds_read_b128 v[114:117], v73
	ds_read_b128 v[118:121], v73 offset:4096
	v_mfma_f32_32x32x16_bf16 v[0:15], v[134:137], v[126:129], v[0:15]
	v_mfma_f32_32x32x16_bf16 v[48:63], v[130:133], v[122:125], v[48:63]
	v_mfma_f32_32x32x16_bf16 v[16:31], v[130:133], v[126:129], v[16:31]
	v_mfma_f32_32x32x16_bf16 v[32:47], v[134:137], v[122:125], v[32:47]
	ds_read_b128 v[122:125], v95
	ds_read_b128 v[126:129], v95 offset:4096
	ds_read_b128 v[130:133], v96
	ds_read_b128 v[134:137], v96 offset:4096
	s_waitcnt vmcnt(6)
	s_barrier
; template <int NI>
; DEVINL void gemm_kloop(const bf16_t* __restrict__ A, int lda, const bf16_t* __restrict__ Bt, int ldb, int K, int m0, int n0,
;                        unsigned char* lds, f32x16 (&acc)[NI][2]) {
;     ...
;     const int nt = K >> 6;
;     asm volatile("s_waitcnt lgkmcnt(0)" ::: "memory");
;     __builtin_amdgcn_s_barrier();
;     GEMM_ISSUE(0, 0);
;     if (nt > 1) GEMM_ISSUE(1, 1);
;     const int sw = (r >> 1) & 7;
;     int o4[4];
; #pragma unroll
;     for (int ks = 0; ks < 4; ++ks) o4[ks] = ((ks * 2 + h) ^ sw) * 16;
;     int cur = 0;
;     auto compute = [&](int st_) {
;         const unsigned char* pa = lds + st_ * STAGE + (wm * 64 + r) * 128;
;         const unsigned char* pb = lds + st_ * STAGE + A_ST + (wn * 32 * NI + r) * 128;
;         bf16x8 af[2][2], bfr[2][NI];
; #pragma unroll
;         for (int i = 0; i < 2; ++i) af[0][i] = *(const bf16x8*)(pa + i * 32 * 128 + o4[0]);
; #pragma unroll
;         for (int i = 0; i < NI; ++i) bfr[0][i] = *(const bf16x8*)(pb + i * 32 * 128 + o4[0]);
; #pragma unroll
;         for (int ks = 0; ks < 4; ++ks) {
;             if (ks < 3) {
; #pragma unroll
;                 for (int i = 0; i < 2; ++i) af[(ks + 1) & 1][i] = *(const bf16x8*)(pa + i * 32 * 128 + o4[ks + 1]);
; #pragma unroll
;                 for (int i = 0; i < NI; ++i) bfr[(ks + 1) & 1][i] = *(const bf16x8*)(pb + i * 32 * 128 + o4[ks + 1]);
;             }
; #pragma unroll
;             for (int ni = 0; ni < NI; ++ni)
; #pragma unroll
;                 for (int mi = 0; mi < 2; ++mi) acc[ni][mi] = MFMA32(bfr[ks & 1][ni], af[ks & 1][mi], acc[ni][mi]);
;         }
;     };
;     int t = 0;
;     for (; t + 2 < nt; ++t) {
;         if (NI == 2) asm volatile("s_waitcnt vmcnt(6)" ::: "memory"); else asm volatile("s_waitcnt vmcnt(5)" ::: "memory");
;         __builtin_amdgcn_s_barrier();
;         { const int s2 = (cur >= 1) ? cur - 1 : 2; GEMM_ISSUE(s2, t + 2); }
;         compute(cur);
;         cur = (cur == 2) ? 0 : cur + 1;
;     }
;     if (nt >= 2) {
;         if (NI == 2) asm volatile("s_waitcnt vmcnt(6)" ::: "memory"); else asm volatile("s_waitcnt vmcnt(5)" ::: "memory");
;         __builtin_amdgcn_s_barrier();
;         compute(cur);
;         cur = (cur == 2) ? 0 : cur + 1;
;     }
;     asm volatile("s_waitcnt vmcnt(0)" ::: "memory");
;     __builtin_amdgcn_s_barrier();
;     compute(cur);
	s_waitcnt lgkmcnt(0)
	v_mfma_f32_32x32x16_bf16 v[0:15], v[118:121], v[110:113], v[0:15]
	v_mfma_f32_32x32x16_bf16 v[48:63], v[114:117], v[106:109], v[48:63]
	v_mfma_f32_32x32x16_bf16 v[16:31], v[114:117], v[110:113], v[16:31]
	v_mfma_f32_32x32x16_bf16 v[32:47], v[118:121], v[106:109], v[32:47]
	v_lshl_add_u64 v[106:107], v[74:75], 0, s[24:25]
	global_load_lds_dwordx4 v[106:107], off
	v_lshl_add_u64 v[106:107], v[74:75], 0, s[36:37]
	s_mov_b32 m0, s11
	s_nop 0
	global_load_lds_dwordx4 v[106:107], off
	v_mfma_f32_32x32x16_bf16 v[0:15], v[134:137], v[126:129], v[0:15]
	s_mov_b32 m0, s12
	s_nop 0
	global_load_lds_dwordx4 v[100:101], off
	v_lshl_add_u64 v[100:101], v[74:75], 0, s[16:17]
	s_mov_b32 m0, s13
	v_readfirstlane_b32 s16, v92
	global_load_lds_dwordx4 v[100:101], off
	v_lshl_add_u64 v[100:101], v[76:77], 0, s[24:25]
	s_mov_b32 m0, s14
	v_mfma_f32_32x32x16_bf16 v[48:63], v[130:133], v[122:125], v[48:63]
	global_load_lds_dwordx4 v[100:101], off
	v_lshl_add_u64 v[100:101], v[76:77], 0, s[36:37]
	s_mov_b32 m0, s20
	s_mov_b64 s[24:25], 0x600
	global_load_lds_dwordx4 v[100:101], off
	v_mfma_f32_32x32x16_bf16 v[16:31], v[130:133], v[126:129], v[16:31]
	s_mov_b64 s[36:37], 0x20600
	s_mov_b32 m0, s21
	v_readfirstlane_b32 s17, v91
	v_mfma_f32_32x32x16_bf16 v[32:47], v[134:137], v[122:125], v[32:47]
	ds_read_b128 v[98:101], v80
	ds_read_b128 v[102:105], v80 offset:4096
	ds_read_b128 v[106:109], v64 offset:32768
	ds_read_b128 v[110:113], v64 offset:36864
	ds_read_b128 v[114:117], v81
	ds_read_b128 v[118:121], v81 offset:4096
	ds_read_b128 v[122:125], v82 offset:32768
	ds_read_b128 v[126:129], v82 offset:36864
	s_waitcnt lgkmcnt(0)
	v_mfma_f32_32x32x16_bf16 v[0:15], v[110:113], v[102:105], v[0:15]
	v_mfma_f32_32x32x16_bf16 v[48:63], v[106:109], v[98:101], v[48:63]
	v_mfma_f32_32x32x16_bf16 v[16:31], v[106:109], v[102:105], v[16:31]
	v_mfma_f32_32x32x16_bf16 v[32:47], v[110:113], v[98:101], v[32:47]
	ds_read_b128 v[98:101], v83
	ds_read_b128 v[102:105], v83 offset:4096
	ds_read_b128 v[106:109], v84 offset:32768
	ds_read_b128 v[110:113], v84 offset:36864
	v_mfma_f32_32x32x16_bf16 v[0:15], v[126:129], v[118:121], v[0:15]
	v_mfma_f32_32x32x16_bf16 v[48:63], v[122:125], v[114:117], v[48:63]
	v_mfma_f32_32x32x16_bf16 v[16:31], v[122:125], v[118:121], v[16:31]
	v_mfma_f32_32x32x16_bf16 v[32:47], v[126:129], v[114:117], v[32:47]
	ds_read_b128 v[114:117], v85
	ds_read_b128 v[118:121], v85 offset:4096
	ds_read_b128 v[122:125], v86 offset:32768
	ds_read_b128 v[126:129], v86 offset:36864
	s_waitcnt vmcnt(6)
	s_barrier
	s_waitcnt lgkmcnt(0)
	v_mfma_f32_32x32x16_bf16 v[0:15], v[110:113], v[102:105], v[0:15]
	v_mfma_f32_32x32x16_bf16 v[48:63], v[106:109], v[98:101], v[48:63]
	v_mfma_f32_32x32x16_bf16 v[16:31], v[106:109], v[102:105], v[16:31]
	v_mfma_f32_32x32x16_bf16 v[32:47], v[110:113], v[98:101], v[32:47]
	v_lshl_add_u64 v[98:99], v[74:75], 0, s[24:25]
	global_load_lds_dwordx4 v[98:99], off
	v_lshl_add_u64 v[98:99], v[74:75], 0, s[36:37]
	s_mov_b32 m0, s16
	s_nop 0
	global_load_lds_dwordx4 v[98:99], off
	v_mfma_f32_32x32x16_bf16 v[0:15], v[126:129], v[118:121], v[0:15]
	v_lshl_add_u64 v[98:99], v[74:75], 0, s[18:19]
	s_mov_b32 m0, s17
	v_readfirstlane_b32 s18, v90
	global_load_lds_dwordx4 v[98:99], off
	v_lshl_add_u64 v[98:99], v[74:75], 0, s[50:51]
	s_mov_b32 m0, s18
	v_readfirstlane_b32 s19, v88
	global_load_lds_dwordx4 v[98:99], off
	v_lshl_add_u64 v[90:91], v[76:77], 0, s[24:25]
	s_mov_b32 m0, s19
	v_readfirstlane_b32 s24, v87
	global_load_lds_dwordx4 v[90:91], off
	v_lshl_add_u64 v[88:89], v[76:77], 0, s[36:37]
	s_mov_b32 m0, s24
	v_mfma_f32_32x32x16_bf16 v[48:63], v[122:125], v[114:117], v[48:63]
	global_load_lds_dwordx4 v[88:89], off
	s_mov_b64 s[36:37], 0x680
	s_mov_b64 s[50:51], 0x20680
	s_mov_b32 m0, s10
	v_mfma_f32_32x32x16_bf16 v[16:31], v[122:125], v[118:121], v[16:31]
	v_mfma_f32_32x32x16_bf16 v[32:47], v[126:129], v[114:117], v[32:47]
	ds_read_b128 v[88:91], v80 offset:49152
	ds_read_b128 v[98:101], v80 offset:53248
	ds_read_b128 v[102:105], v93
	ds_read_b128 v[106:109], v93 offset:4096
	ds_read_b128 v[110:113], v81 offset:49152
	ds_read_b128 v[114:117], v81 offset:53248
	ds_read_b128 v[118:121], v94
	ds_read_b128 v[122:125], v94 offset:4096
	s_waitcnt lgkmcnt(0)
	v_mfma_f32_32x32x16_bf16 v[0:15], v[106:109], v[98:101], v[0:15]
	v_mfma_f32_32x32x16_bf16 v[48:63], v[102:105], v[88:91], v[48:63]
	v_mfma_f32_32x32x16_bf16 v[16:31], v[102:105], v[98:101], v[16:31]
	v_mfma_f32_32x32x16_bf16 v[32:47], v[106:109], v[88:91], v[32:47]
	ds_read_b128 v[88:91], v83 offset:49152
	ds_read_b128 v[98:101], v83 offset:53248
	ds_read_b128 v[102:105], v66
	ds_read_b128 v[106:109], v66 offset:4096
	v_mfma_f32_32x32x16_bf16 v[0:15], v[122:125], v[114:117], v[0:15]
	v_mfma_f32_32x32x16_bf16 v[48:63], v[118:121], v[110:113], v[48:63]
	v_mfma_f32_32x32x16_bf16 v[16:31], v[118:121], v[114:117], v[16:31]
	v_mfma_f32_32x32x16_bf16 v[32:47], v[122:125], v[110:113], v[32:47]
	ds_read_b128 v[110:113], v85 offset:49152
	ds_read_b128 v[114:117], v85 offset:53248
	ds_read_b128 v[118:121], v67
	ds_read_b128 v[122:125], v67 offset:4096
	s_waitcnt vmcnt(6)
	s_barrier
; template <int NI>
; DEVINL void gemm_kloop(const bf16_t* __restrict__ A, int lda, const bf16_t* __restrict__ Bt, int ldb, int K, int m0, int n0,
;                        unsigned char* lds, f32x16 (&acc)[NI][2]) {
;     ...
;     const int nt = K >> 6;
;     asm volatile("s_waitcnt lgkmcnt(0)" ::: "memory");
;     __builtin_amdgcn_s_barrier();
;     GEMM_ISSUE(0, 0);
;     if (nt > 1) GEMM_ISSUE(1, 1);
;     const int sw = (r >> 1) & 7;
;     int o4[4];
; #pragma unroll
;     for (int ks = 0; ks < 4; ++ks) o4[ks] = ((ks * 2 + h) ^ sw) * 16;
;     int cur = 0;
;     auto compute = [&](int st_) {
;         const unsigned char* pa = lds + st_ * STAGE + (wm * 64 + r) * 128;
;         const unsigned char* pb = lds + st_ * STAGE + A_ST + (wn * 32 * NI + r) * 128;
;         bf16x8 af[2][2], bfr[2][NI];
; #pragma unroll
;         for (int i = 0; i < 2; ++i) af[0][i] = *(const bf16x8*)(pa + i * 32 * 128 + o4[0]);
; #pragma unroll
;         for (int i = 0; i < NI; ++i) bfr[0][i] = *(const bf16x8*)(pb + i * 32 * 128 + o4[0]);
; #pragma unroll
;         for (int ks = 0; ks < 4; ++ks) {
;             if (ks < 3) {
; #pragma unroll
;                 for (int i = 0; i < 2; ++i) af[(ks + 1) & 1][i] = *(const bf16x8*)(pa + i * 32 * 128 + o4[ks + 1]);
; #pragma unroll
;                 for (int i = 0; i < NI; ++i) bfr[(ks + 1) & 1][i] = *(const bf16x8*)(pb + i * 32 * 128 + o4[ks + 1]);
;             }
; #pragma unroll
;             for (int ni = 0; ni < NI; ++ni)
; #pragma unroll
;                 for (int mi = 0; mi < 2; ++mi) acc[ni][mi] = MFMA32(bfr[ks & 1][ni], af[ks & 1][mi], acc[ni][mi]);
;         }
;     };
;     int t = 0;
;     for (; t + 2 < nt; ++t) {
;         if (NI == 2) asm volatile("s_waitcnt vmcnt(6)" ::: "memory"); else asm volatile("s_waitcnt vmcnt(5)" ::: "memory");
;         __builtin_amdgcn_s_barrier();
;         { const int s2 = (cur >= 1) ? cur - 1 : 2; GEMM_ISSUE(s2, t + 2); }
;         compute(cur);
;         cur = (cur == 2) ? 0 : cur + 1;
;     }
;     if (nt >= 2) {
;         if (NI == 2) asm volatile("s_waitcnt vmcnt(6)" ::: "memory"); else asm volatile("s_waitcnt vmcnt(5)" ::: "memory");
;         __builtin_amdgcn_s_barrier();
;         compute(cur);
;         cur = (cur == 2) ? 0 : cur + 1;
;     }
;     asm volatile("s_waitcnt vmcnt(0)" ::: "memory");
;     __builtin_amdgcn_s_barrier();
;     compute(cur);
	s_waitcnt lgkmcnt(0)
	v_mfma_f32_32x32x16_bf16 v[0:15], v[106:109], v[98:101], v[0:15]
	v_mfma_f32_32x32x16_bf16 v[48:63], v[102:105], v[88:91], v[48:63]
	v_mfma_f32_32x32x16_bf16 v[16:31], v[102:105], v[98:101], v[16:31]
	v_mfma_f32_32x32x16_bf16 v[32:47], v[106:109], v[88:91], v[32:47]
	v_lshl_add_u64 v[88:89], v[74:75], 0, s[36:37]
	global_load_lds_dwordx4 v[88:89], off
	v_lshl_add_u64 v[88:89], v[74:75], 0, s[50:51]
	s_mov_b32 m0, s9
	s_nop 0
	global_load_lds_dwordx4 v[88:89], off
	v_mfma_f32_32x32x16_bf16 v[0:15], v[122:125], v[114:117], v[0:15]
	v_lshl_add_u64 v[88:89], v[74:75], 0, s[52:53]
	s_mov_b64 s[52:53], 0x60680
	s_mov_b32 m0, s8
	s_mov_b64 s[8:9], 0x60000
	global_load_lds_dwordx4 v[88:89], off
	v_lshl_add_u64 v[88:89], v[74:75], 0, s[52:53]
	s_mov_b32 m0, s7
	v_mfma_f32_32x32x16_bf16 v[48:63], v[118:121], v[110:113], v[48:63]
	global_load_lds_dwordx4 v[88:89], off
	v_lshl_add_u64 v[88:89], v[76:77], 0, s[36:37]
	s_mov_b32 m0, s6
	s_mov_b64 s[6:7], 0x700
	global_load_lds_dwordx4 v[88:89], off
	v_lshl_add_u64 v[88:89], v[76:77], 0, s[50:51]
	s_mov_b32 m0, s5
	v_mfma_f32_32x32x16_bf16 v[16:31], v[118:121], v[114:117], v[16:31]
	global_load_lds_dwordx4 v[88:89], off
	s_mov_b32 m0, s15
	s_mov_b64 s[36:37], 0x40700
	v_mfma_f32_32x32x16_bf16 v[32:47], v[122:125], v[110:113], v[32:47]
	ds_read_b128 v[88:91], v68
	ds_read_b128 v[98:101], v68 offset:4096
	ds_read_b128 v[102:105], v69
	ds_read_b128 v[106:109], v69 offset:4096
	ds_read_b128 v[110:113], v70
	ds_read_b128 v[114:117], v70 offset:4096
	ds_read_b128 v[118:121], v71
	ds_read_b128 v[122:125], v71 offset:4096
	s_waitcnt lgkmcnt(0)
	v_mfma_f32_32x32x16_bf16 v[0:15], v[106:109], v[98:101], v[0:15]
	v_mfma_f32_32x32x16_bf16 v[48:63], v[102:105], v[88:91], v[48:63]
	v_mfma_f32_32x32x16_bf16 v[16:31], v[102:105], v[98:101], v[16:31]
	v_mfma_f32_32x32x16_bf16 v[32:47], v[106:109], v[88:91], v[32:47]
	ds_read_b128 v[88:91], v72
	ds_read_b128 v[98:101], v72 offset:4096
	ds_read_b128 v[102:105], v73
	ds_read_b128 v[106:109], v73 offset:4096
	v_mfma_f32_32x32x16_bf16 v[0:15], v[122:125], v[114:117], v[0:15]
	v_mfma_f32_32x32x16_bf16 v[48:63], v[118:121], v[110:113], v[48:63]
	v_mfma_f32_32x32x16_bf16 v[16:31], v[118:121], v[114:117], v[16:31]
	v_mfma_f32_32x32x16_bf16 v[32:47], v[122:125], v[110:113], v[32:47]
	ds_read_b128 v[110:113], v95
	ds_read_b128 v[114:117], v95 offset:4096
	ds_read_b128 v[118:121], v96
	ds_read_b128 v[122:125], v96 offset:4096
	s_waitcnt vmcnt(6)
	s_barrier
	s_waitcnt lgkmcnt(0)
	v_mfma_f32_32x32x16_bf16 v[0:15], v[106:109], v[98:101], v[0:15]
	v_mfma_f32_32x32x16_bf16 v[48:63], v[102:105], v[88:91], v[48:63]
	v_mfma_f32_32x32x16_bf16 v[16:31], v[102:105], v[98:101], v[16:31]
	v_mfma_f32_32x32x16_bf16 v[32:47], v[106:109], v[88:91], v[32:47]
	v_lshl_add_u64 v[88:89], v[74:75], 0, s[6:7]
	global_load_lds_dwordx4 v[88:89], off
	v_lshl_add_u64 v[88:89], v[74:75], 0, s[54:55]
	s_mov_b32 m0, s11
	s_mov_b64 s[10:11], 0x40000
	global_load_lds_dwordx4 v[88:89], off
	v_mfma_f32_32x32x16_bf16 v[0:15], v[122:125], v[114:117], v[0:15]
	v_lshl_add_u64 v[88:89], v[74:75], 0, s[36:37]
	s_mov_b64 s[36:37], 0x60700
	s_mov_b32 m0, s12
	s_nop 0
	global_load_lds_dwordx4 v[88:89], off
	v_lshl_add_u64 v[88:89], v[74:75], 0, s[36:37]
	s_mov_b32 m0, s13
	v_mfma_f32_32x32x16_bf16 v[48:63], v[118:121], v[110:113], v[48:63]
	global_load_lds_dwordx4 v[88:89], off
	v_lshl_add_u64 v[88:89], v[76:77], 0, s[6:7]
	s_mov_b32 m0, s14
	s_mov_b64 s[6:7], 0x40780
	global_load_lds_dwordx4 v[88:89], off
	v_lshl_add_u64 v[88:89], v[76:77], 0, s[54:55]
	s_mov_b32 m0, s20
	v_mfma_f32_32x32x16_bf16 v[16:31], v[118:121], v[114:117], v[16:31]
	global_load_lds_dwordx4 v[88:89], off
	s_mov_b32 m0, s21
	s_mov_b64 s[20:21], 0x60080
	v_mfma_f32_32x32x16_bf16 v[32:47], v[122:125], v[110:113], v[32:47]
	ds_read_b128 v[88:91], v80
	ds_read_b128 v[98:101], v80 offset:4096
	ds_read_b128 v[102:105], v64 offset:32768
	ds_read_b128 v[106:109], v64 offset:36864
	ds_read_b128 v[110:113], v81
	ds_read_b128 v[114:117], v81 offset:4096
	ds_read_b128 v[118:121], v82 offset:32768
	ds_read_b128 v[122:125], v82 offset:36864
	s_waitcnt lgkmcnt(0)
	v_mfma_f32_32x32x16_bf16 v[0:15], v[106:109], v[98:101], v[0:15]
	v_mfma_f32_32x32x16_bf16 v[48:63], v[102:105], v[88:91], v[48:63]
	v_mfma_f32_32x32x16_bf16 v[16:31], v[102:105], v[98:101], v[16:31]
	v_mfma_f32_32x32x16_bf16 v[32:47], v[106:109], v[88:91], v[32:47]
	ds_read_b128 v[88:91], v83
	ds_read_b128 v[98:101], v83 offset:4096
	ds_read_b128 v[102:105], v84 offset:32768
	ds_read_b128 v[106:109], v84 offset:36864
	v_mfma_f32_32x32x16_bf16 v[0:15], v[122:125], v[114:117], v[0:15]
	v_mfma_f32_32x32x16_bf16 v[48:63], v[118:121], v[110:113], v[48:63]
	v_mfma_f32_32x32x16_bf16 v[16:31], v[118:121], v[114:117], v[16:31]
	v_mfma_f32_32x32x16_bf16 v[32:47], v[122:125], v[110:113], v[32:47]
	ds_read_b128 v[110:113], v85
	ds_read_b128 v[114:117], v85 offset:4096
	ds_read_b128 v[118:121], v86 offset:32768
	ds_read_b128 v[122:125], v86 offset:36864
	s_waitcnt vmcnt(6)
	s_barrier
; template <int NI>
; DEVINL void gemm_kloop(const bf16_t* __restrict__ A, int lda, const bf16_t* __restrict__ Bt, int ldb, int K, int m0, int n0,
;                        unsigned char* lds, f32x16 (&acc)[NI][2]) {
;     ...
;     const int nt = K >> 6;
;     asm volatile("s_waitcnt lgkmcnt(0)" ::: "memory");
;     __builtin_amdgcn_s_barrier();
;     GEMM_ISSUE(0, 0);
;     if (nt > 1) GEMM_ISSUE(1, 1);
;     const int sw = (r >> 1) & 7;
;     int o4[4];
; #pragma unroll
;     for (int ks = 0; ks < 4; ++ks) o4[ks] = ((ks * 2 + h) ^ sw) * 16;
;     int cur = 0;
;     auto compute = [&](int st_) {
;         const unsigned char* pa = lds + st_ * STAGE + (wm * 64 + r) * 128;
;         const unsigned char* pb = lds + st_ * STAGE + A_ST + (wn * 32 * NI + r) * 128;
;         bf16x8 af[2][2], bfr[2][NI];
; #pragma unroll
;         for (int i = 0; i < 2; ++i) af[0][i] = *(const bf16x8*)(pa + i * 32 * 128 + o4[0]);
; #pragma unroll
;         for (int i = 0; i < NI; ++i) bfr[0][i] = *(const bf16x8*)(pb + i * 32 * 128 + o4[0]);
; #pragma unroll
;         for (int ks = 0; ks < 4; ++ks) {
;             if (ks < 3) {
; #pragma unroll
;                 for (int i = 0; i < 2; ++i) af[(ks + 1) & 1][i] = *(const bf16x8*)(pa + i * 32 * 128 + o4[ks + 1]);
; #pragma unroll
;                 for (int i = 0; i < NI; ++i) bfr[(ks + 1) & 1][i] = *(const bf16x8*)(pb + i * 32 * 128 + o4[ks + 1]);
;             }
; #pragma unroll
;             for (int ni = 0; ni < NI; ++ni)
; #pragma unroll
;                 for (int mi = 0; mi < 2; ++mi) acc[ni][mi] = MFMA32(bfr[ks & 1][ni], af[ks & 1][mi], acc[ni][mi]);
;         }
;     };
;     int t = 0;
;     for (; t + 2 < nt; ++t) {
;         if (NI == 2) asm volatile("s_waitcnt vmcnt(6)" ::: "memory"); else asm volatile("s_waitcnt vmcnt(5)" ::: "memory");
;         __builtin_amdgcn_s_barrier();
;         { const int s2 = (cur >= 1) ? cur - 1 : 2; GEMM_ISSUE(s2, t + 2); }
;         compute(cur);
;         cur = (cur == 2) ? 0 : cur + 1;
;     }
;     if (nt >= 2) {
;         if (NI == 2) asm volatile("s_waitcnt vmcnt(6)" ::: "memory"); else asm volatile("s_waitcnt vmcnt(5)" ::: "memory");
;         __builtin_amdgcn_s_barrier();
;         compute(cur);
;         cur = (cur == 2) ? 0 : cur + 1;
;     }
;     asm volatile("s_waitcnt vmcnt(0)" ::: "memory");
;     __builtin_amdgcn_s_barrier();
;     compute(cur);
	s_waitcnt lgkmcnt(0)
	v_mfma_f32_32x32x16_bf16 v[0:15], v[106:109], v[98:101], v[0:15]
	v_mfma_f32_32x32x16_bf16 v[48:63], v[102:105], v[88:91], v[48:63]
	v_mfma_f32_32x32x16_bf16 v[16:31], v[102:105], v[98:101], v[16:31]
	v_mfma_f32_32x32x16_bf16 v[32:47], v[106:109], v[88:91], v[32:47]
	v_lshl_add_u64 v[88:89], v[74:75], 0, vcc
	global_load_lds_dwordx4 v[88:89], off
	v_lshl_add_u64 v[88:89], v[74:75], 0, s[94:95]
	s_mov_b32 m0, s16
	s_nop 0
	global_load_lds_dwordx4 v[88:89], off
	v_mfma_f32_32x32x16_bf16 v[0:15], v[122:125], v[114:117], v[0:15]
	v_lshl_add_u64 v[88:89], v[74:75], 0, s[6:7]
	s_mov_b64 s[6:7], 0x60780
	s_mov_b32 m0, s17
	v_lshl_add_u64 v[74:75], v[74:75], 0, s[6:7]
	global_load_lds_dwordx4 v[88:89], off
	s_mov_b32 m0, s18
	v_mfma_f32_32x32x16_bf16 v[48:63], v[118:121], v[110:113], v[48:63]
	global_load_lds_dwordx4 v[74:75], off
	v_lshl_add_u64 v[74:75], v[76:77], 0, vcc
	s_mov_b32 m0, s19
	s_mov_b64 s[18:19], 0x40080
	global_load_lds_dwordx4 v[74:75], off
	v_lshl_add_u64 v[74:75], v[76:77], 0, s[94:95]
	s_mov_b32 m0, s24
	v_mfma_f32_32x32x16_bf16 v[16:31], v[118:121], v[114:117], v[16:31]
	global_load_lds_dwordx4 v[74:75], off
	s_mov_b64 s[24:25], 0x20100
	v_mfma_f32_32x32x16_bf16 v[32:47], v[122:125], v[110:113], v[32:47]
	ds_read_b128 v[74:77], v80 offset:49152
	ds_read_b128 v[88:91], v80 offset:53248
	ds_read_b128 v[98:101], v93
	ds_read_b128 v[102:105], v93 offset:4096
	ds_read_b128 v[106:109], v81 offset:49152
	ds_read_b128 v[110:113], v81 offset:53248
	ds_read_b128 v[114:117], v94
	ds_read_b128 v[118:121], v94 offset:4096
	s_waitcnt lgkmcnt(0)
	v_mfma_f32_32x32x16_bf16 v[0:15], v[102:105], v[88:91], v[0:15]
	v_mfma_f32_32x32x16_bf16 v[48:63], v[98:101], v[74:77], v[48:63]
	v_mfma_f32_32x32x16_bf16 v[16:31], v[98:101], v[88:91], v[16:31]
	v_mfma_f32_32x32x16_bf16 v[32:47], v[102:105], v[74:77], v[32:47]
	ds_read_b128 v[74:77], v83 offset:49152
	ds_read_b128 v[88:91], v83 offset:53248
	ds_read_b128 v[98:101], v66
	ds_read_b128 v[102:105], v66 offset:4096
	v_mfma_f32_32x32x16_bf16 v[0:15], v[118:121], v[110:113], v[0:15]
	v_mfma_f32_32x32x16_bf16 v[48:63], v[114:117], v[106:109], v[48:63]
	v_mfma_f32_32x32x16_bf16 v[16:31], v[114:117], v[110:113], v[16:31]
	v_mfma_f32_32x32x16_bf16 v[32:47], v[118:121], v[106:109], v[32:47]
	ds_read_b128 v[106:109], v85 offset:49152
	ds_read_b128 v[110:113], v85 offset:53248
	ds_read_b128 v[114:117], v67
	ds_read_b128 v[118:121], v67 offset:4096
	s_waitcnt vmcnt(6)
	s_barrier
	s_waitcnt lgkmcnt(0)
	v_mfma_f32_32x32x16_bf16 v[0:15], v[102:105], v[88:91], v[0:15]
	v_mfma_f32_32x32x16_bf16 v[48:63], v[98:101], v[74:77], v[48:63]
	v_mfma_f32_32x32x16_bf16 v[16:31], v[98:101], v[88:91], v[16:31]
	v_mfma_f32_32x32x16_bf16 v[32:47], v[102:105], v[74:77], v[32:47]
	v_mfma_f32_32x32x16_bf16 v[0:15], v[118:121], v[110:113], v[0:15]
	v_mfma_f32_32x32x16_bf16 v[48:63], v[114:117], v[106:109], v[48:63]
	v_mfma_f32_32x32x16_bf16 v[16:31], v[114:117], v[110:113], v[16:31]
	v_mfma_f32_32x32x16_bf16 v[32:47], v[118:121], v[106:109], v[32:47]
	ds_read_b128 v[74:77], v68
	ds_read_b128 v[88:91], v68 offset:4096
	ds_read_b128 v[98:101], v69
	ds_read_b128 v[66:69], v69 offset:4096
	ds_read_b128 v[102:105], v70
	ds_read_b128 v[106:109], v70 offset:4096
	ds_read_b128 v[110:113], v71
	ds_read_b128 v[114:117], v71 offset:4096
	s_waitcnt lgkmcnt(0)
	v_mfma_f32_32x32x16_bf16 v[0:15], v[66:69], v[88:91], v[0:15]
	v_mfma_f32_32x32x16_bf16 v[48:63], v[98:101], v[74:77], v[48:63]
	v_mfma_f32_32x32x16_bf16 v[16:31], v[98:101], v[88:91], v[16:31]
	v_mfma_f32_32x32x16_bf16 v[32:47], v[66:69], v[74:77], v[32:47]
	ds_read_b128 v[66:69], v72
	ds_read_b128 v[74:77], v72 offset:4096
	ds_read_b128 v[88:91], v73
	ds_read_b128 v[70:73], v73 offset:4096
	v_mfma_f32_32x32x16_bf16 v[0:15], v[114:117], v[106:109], v[0:15]
	v_mfma_f32_32x32x16_bf16 v[48:63], v[110:113], v[102:105], v[48:63]
	v_mfma_f32_32x32x16_bf16 v[16:31], v[110:113], v[106:109], v[16:31]
	v_mfma_f32_32x32x16_bf16 v[32:47], v[114:117], v[102:105], v[32:47]
	ds_read_b128 v[98:101], v95
	ds_read_b128 v[92:95], v95 offset:4096
	ds_read_b128 v[102:105], v96
	ds_read_b128 v[106:109], v96 offset:4096
	s_waitcnt vmcnt(0)
	s_barrier
	s_waitcnt lgkmcnt(0)
	v_mfma_f32_32x32x16_bf16 v[0:15], v[70:73], v[74:77], v[0:15]
	v_mfma_f32_32x32x16_bf16 v[48:63], v[88:91], v[66:69], v[48:63]
	v_mfma_f32_32x32x16_bf16 v[16:31], v[88:91], v[74:77], v[16:31]
	v_mfma_f32_32x32x16_bf16 v[32:47], v[70:73], v[66:69], v[32:47]
	v_mfma_f32_32x32x16_bf16 v[0:15], v[106:109], v[92:95], v[0:15]
	v_mfma_f32_32x32x16_bf16 v[48:63], v[102:105], v[98:101], v[48:63]
	v_mfma_f32_32x32x16_bf16 v[16:31], v[102:105], v[92:95], v[16:31]
	v_mfma_f32_32x32x16_bf16 v[32:47], v[106:109], v[98:101], v[32:47]
	ds_read_b128 v[66:69], v80
	ds_read_b128 v[70:73], v80 offset:4096
	ds_read_b128 v[74:77], v64 offset:32768
	ds_read_b128 v[88:91], v64 offset:36864
	ds_read_b128 v[92:95], v81
	ds_read_b128 v[96:99], v81 offset:4096
	ds_read_b128 v[100:103], v82 offset:32768
	ds_read_b128 v[104:107], v82 offset:36864
	s_waitcnt lgkmcnt(0)
	v_mfma_f32_32x32x16_bf16 v[0:15], v[88:91], v[70:73], v[0:15]
	v_mfma_f32_32x32x16_bf16 v[48:63], v[74:77], v[66:69], v[48:63]
	v_mfma_f32_32x32x16_bf16 v[32:47], v[88:91], v[66:69], v[32:47]
	v_mfma_f32_32x32x16_bf16 v[16:31], v[74:77], v[70:73], v[16:31]
	ds_read_b128 v[66:69], v83
	ds_read_b128 v[70:73], v83 offset:4096
	ds_read_b128 v[74:77], v84 offset:32768
	ds_read_b128 v[80:83], v84 offset:36864
	v_mfma_f32_32x32x16_bf16 v[0:15], v[104:107], v[96:99], v[0:15]
	v_mfma_f32_32x32x16_bf16 v[48:63], v[100:103], v[92:95], v[48:63]
	v_mfma_f32_32x32x16_bf16 v[32:47], v[104:107], v[92:95], v[32:47]
	v_mfma_f32_32x32x16_bf16 v[16:31], v[100:103], v[96:99], v[16:31]
	ds_read_b128 v[88:91], v85
	ds_read_b128 v[92:95], v85 offset:4096
	ds_read_b128 v[96:99], v86 offset:32768
	ds_read_b128 v[84:87], v86 offset:36864
	s_waitcnt lgkmcnt(0)
;     DEVINL bf16_t* U() const { return (bf16_t*)(ws + OFF_Z); }
; #define TID (opq_v((int)threadIdx.x))
; DEVINL unsigned cvt_pk_bf16(float lo, float hi) { const f32x2 v = {lo, hi}; return __builtin_bit_cast(unsigned, __builtin_convertvector(v, bf16x2v)); }
; DEVINL void store_rows_via_lds(unsigned char* lds, const u32x2 (&pk)[2][2][4], bf16_t* out_row0, int ld) {
;     const int tid = TID, lane = tid & 63, w = tid >> 6, r = lane & 31, h = lane >> 5;
;     unsigned char* reg = lds + w * (64 * 144);
;     __syncthreads();
; DEVINL void phase_up(const Ctx& c, unsigned char* lds) {
;     ...
;         const int mbase = tm * 256 + wm * 64, nbase = tn * 128 + wn * 64;
;         {
;             u32x2 pku[2][2][4];
; #pragma unroll
;             for (int mi = 0; mi < 2; ++mi)
; #pragma unroll
;                 for (int ni = 0; ni < 2; ++ni)
; #pragma unroll
;                     for (int g = 0; g < 4; ++g) {
;                         float v[4];
; #pragma unroll
;                         for (int j = 0; j < 4; ++j) { const float a = fmaxf(acc[ni][mi][4 * g + j], 0.f); v[j] = a * a; }
;                         pku[mi][ni][g][0] = cvt_pk_bf16(v[0], v[1]); pku[mi][ni][g][1] = cvt_pk_bf16(v[2], v[3]);
;                     }
;             store_rows_via_lds(lds, pku, c.U() + (size_t)mbase * DFF + nbase, DFF);
	v_mfma_f32_32x32x16_bf16 v[0:15], v[80:83], v[70:73], v[0:15]
	v_mfma_f32_32x32x16_bf16 v[48:63], v[74:77], v[66:69], v[48:63]
	v_mfma_f32_32x32x16_bf16 v[32:47], v[80:83], v[66:69], v[32:47]
	v_or_b32_e32 v66, s4, v78
	v_ashrrev_i32_e32 v67, 31, v66
	v_mfma_f32_32x32x16_bf16 v[16:31], v[74:77], v[70:73], v[16:31]
	v_mfma_f32_32x32x16_bf16 v[0:15], v[84:87], v[92:95], v[0:15]
	v_mfma_f32_32x32x16_bf16 v[48:63], v[96:99], v[88:91], v[48:63]
	s_nop 10
	v_max_f32_e32 v0, v0, v0
	v_max_f32_e32 v1, v1, v1
	v_max_f32_e32 v2, v2, v2
	v_max_f32_e32 v3, v3, v3
	v_max_f32_e32 v0, 0, v0
	v_max_f32_e32 v1, 0, v1
	v_max_f32_e32 v2, 0, v2
	v_mfma_f32_32x32x16_bf16 v[32:47], v[84:87], v[88:91], v[32:47]
	v_max_f32_e32 v3, 0, v3
	v_mul_f32_e64 v0, v0, v0
	v_mul_f32_e64 v1, v1, v1
	v_mul_f32_e64 v2, v2, v2
	v_mul_f32_e64 v3, v3, v3
	v_cvt_pk_bf16_f32 v0, v0, v1
	v_cvt_pk_bf16_f32 v1, v2, v3
	v_max_f32_e32 v2, v4, v4
	v_max_f32_e32 v3, v5, v5
	v_mfma_f32_32x32x16_bf16 v[16:31], v[96:99], v[92:95], v[16:31]
	v_max_f32_e32 v4, v6, v6
	v_max_f32_e32 v5, v7, v7
	v_max_f32_e32 v2, 0, v2
	v_max_f32_e32 v3, 0, v3
	v_max_f32_e32 v4, 0, v4
	v_max_f32_e32 v5, 0, v5
	v_pk_mul_f32 v[2:3], v[2:3], v[2:3]
	v_pk_mul_f32 v[4:5], v[4:5], v[4:5]
	v_cvt_pk_bf16_f32 v2, v2, v3
	v_cvt_pk_bf16_f32 v3, v4, v5
	v_max_f32_e32 v4, v8, v8
	v_max_f32_e32 v5, v9, v9
	v_max_f32_e32 v6, v10, v10
	v_max_f32_e32 v7, v11, v11
	v_max_f32_e32 v48, v48, v48
	v_max_f32_e32 v49, v49, v49
	v_max_f32_e32 v50, v50, v50
	v_max_f32_e32 v51, v51, v51
	v_max_f32_e32 v32, v32, v32
	v_max_f32_e32 v33, v33, v33
	v_max_f32_e32 v34, v34, v34
	v_max_f32_e32 v35, v35, v35
	v_max_f32_e32 v4, 0, v4
	v_max_f32_e32 v5, 0, v5
	v_max_f32_e32 v6, 0, v6
	v_max_f32_e32 v7, 0, v7
	v_max_f32_e32 v48, 0, v48
	v_max_f32_e32 v49, 0, v49
	v_max_f32_e32 v50, 0, v50
	v_max_f32_e32 v51, 0, v51
	v_max_f32_e32 v32, 0, v32
	v_max_f32_e32 v33, 0, v33
	v_max_f32_e32 v34, 0, v34
	v_max_f32_e32 v35, 0, v35
	v_max_f32_e32 v16, v16, v16
	v_max_f32_e32 v17, v17, v17
	v_max_f32_e32 v18, v18, v18
	v_max_f32_e32 v19, v19, v19
	v_pk_mul_f32 v[4:5], v[4:5], v[4:5]
	v_pk_mul_f32 v[6:7], v[6:7], v[6:7]
	v_pk_mul_f32 v[48:49], v[48:49], v[48:49]
	v_pk_mul_f32 v[50:51], v[50:51], v[50:51]
	v_pk_mul_f32 v[32:33], v[32:33], v[32:33]
	v_pk_mul_f32 v[34:35], v[34:35], v[34:35]
	v_max_f32_e32 v16, 0, v16
	v_max_f32_e32 v17, 0, v17
	v_max_f32_e32 v18, 0, v18
	v_max_f32_e32 v19, 0, v19
	v_cvt_pk_bf16_f32 v4, v4, v5
	v_cvt_pk_bf16_f32 v5, v6, v7
	v_max_f32_e32 v6, v12, v12
	v_max_f32_e32 v7, v13, v13
	v_max_f32_e32 v8, v14, v14
	v_max_f32_e32 v9, v15, v15
	v_cvt_pk_bf16_f32 v48, v48, v49
	v_cvt_pk_bf16_f32 v49, v50, v51
	v_max_f32_e32 v50, v52, v52
	v_max_f32_e32 v51, v53, v53
	v_max_f32_e32 v52, v54, v54
	v_max_f32_e32 v53, v55, v55
	v_cvt_pk_bf16_f32 v32, v32, v33
	v_cvt_pk_bf16_f32 v33, v34, v35
	v_max_f32_e32 v34, v36, v36
	v_max_f32_e32 v35, v37, v37
	v_max_f32_e32 v36, v38, v38
	v_max_f32_e32 v37, v39, v39
	v_pk_mul_f32 v[16:17], v[16:17], v[16:17]
	v_pk_mul_f32 v[18:19], v[18:19], v[18:19]
	v_max_f32_e32 v6, 0, v6
	v_max_f32_e32 v7, 0, v7
	v_max_f32_e32 v8, 0, v8
	v_max_f32_e32 v9, 0, v9
	v_max_f32_e32 v50, 0, v50
	v_max_f32_e32 v51, 0, v51
	v_max_f32_e32 v52, 0, v52
	v_max_f32_e32 v53, 0, v53
	v_max_f32_e32 v34, 0, v34
	v_max_f32_e32 v35, 0, v35
	v_max_f32_e32 v36, 0, v36
	v_max_f32_e32 v37, 0, v37
	v_cvt_pk_bf16_f32 v16, v16, v17
	v_cvt_pk_bf16_f32 v17, v18, v19
	v_max_f32_e32 v18, v20, v20
	v_max_f32_e32 v19, v21, v21
	v_max_f32_e32 v20, v22, v22
	v_max_f32_e32 v21, v23, v23
	v_pk_mul_f32 v[6:7], v[6:7], v[6:7]
	v_pk_mul_f32 v[8:9], v[8:9], v[8:9]
	v_pk_mul_f32 v[50:51], v[50:51], v[50:51]
	v_pk_mul_f32 v[52:53], v[52:53], v[52:53]
	v_pk_mul_f32 v[34:35], v[34:35], v[34:35]
	v_pk_mul_f32 v[36:37], v[36:37], v[36:37]
	v_max_f32_e32 v18, 0, v18
	v_max_f32_e32 v19, 0, v19
	v_max_f32_e32 v20, 0, v20
	v_max_f32_e32 v21, 0, v21
	v_cvt_pk_bf16_f32 v6, v6, v7
	v_cvt_pk_bf16_f32 v7, v8, v9
	v_add_u32_e32 v8, s1, v79
	v_lshlrev_b64 v[10:11], 13, v[66:67]
	v_cvt_pk_bf16_f32 v50, v50, v51
	v_cvt_pk_bf16_f32 v51, v52, v53
	v_max_f32_e32 v52, v56, v56
	v_max_f32_e32 v53, v57, v57
	v_max_f32_e32 v54, v58, v58
	v_max_f32_e32 v55, v59, v59
	v_cvt_pk_bf16_f32 v34, v34, v35
	v_cvt_pk_bf16_f32 v35, v36, v37
	v_max_f32_e32 v36, v40, v40
	v_max_f32_e32 v37, v41, v41
	v_max_f32_e32 v38, v42, v42
	v_max_f32_e32 v39, v43, v43
	v_pk_mul_f32 v[18:19], v[18:19], v[18:19]
	v_pk_mul_f32 v[20:21], v[20:21], v[20:21]
	v_lshl_add_u64 v[10:11], s[28:29], 0, v[10:11]
	v_ashrrev_i32_e32 v9, 31, v8
	v_max_f32_e32 v52, 0, v52
	v_max_f32_e32 v53, 0, v53
	v_max_f32_e32 v54, 0, v54
	v_max_f32_e32 v55, 0, v55
	v_max_f32_e32 v36, 0, v36
	v_max_f32_e32 v37, 0, v37
	v_max_f32_e32 v38, 0, v38
	v_max_f32_e32 v39, 0, v39
	v_cvt_pk_bf16_f32 v18, v18, v19
	v_cvt_pk_bf16_f32 v19, v20, v21
	v_max_f32_e32 v20, v24, v24
	v_max_f32_e32 v21, v25, v25
	v_max_f32_e32 v22, v26, v26
	v_max_f32_e32 v23, v27, v27
	v_lshl_add_u64 v[8:9], v[8:9], 1, v[10:11]
	v_mov_b32_e32 v10, v160
	v_pk_mul_f32 v[52:53], v[52:53], v[52:53]
	v_pk_mul_f32 v[54:55], v[54:55], v[54:55]
	v_pk_mul_f32 v[36:37], v[36:37], v[36:37]
	v_pk_mul_f32 v[38:39], v[38:39], v[38:39]
	v_max_f32_e32 v20, 0, v20
	v_max_f32_e32 v21, 0, v21
	v_max_f32_e32 v22, 0, v22
	v_max_f32_e32 v23, 0, v23
	v_cvt_pk_bf16_f32 v52, v52, v53
	v_lshrrev_b32_e32 v11, 6, v10
	v_cvt_pk_bf16_f32 v53, v54, v55
	v_max_f32_e32 v54, v60, v60
	v_max_f32_e32 v55, v61, v61
	v_max_f32_e32 v56, v62, v62
	v_max_f32_e32 v57, v63, v63
	v_cvt_pk_bf16_f32 v36, v36, v37
	v_cvt_pk_bf16_f32 v37, v38, v39
	v_max_f32_e32 v38, v44, v44
	v_max_f32_e32 v39, v45, v45
	v_max_f32_e32 v40, v46, v46
	v_max_f32_e32 v41, v47, v47
	v_pk_mul_f32 v[20:21], v[20:21], v[20:21]
	v_pk_mul_f32 v[22:23], v[22:23], v[22:23]
	v_and_b32_e32 v12, 31, v10
	v_mul_lo_u32 v11, v11, s38
	v_lshrrev_b32_e32 v13, 2, v10
	v_max_f32_e32 v54, 0, v54
	v_max_f32_e32 v55, 0, v55
	v_max_f32_e32 v56, 0, v56
	v_max_f32_e32 v57, 0, v57
	v_max_f32_e32 v38, 0, v38
	v_max_f32_e32 v39, 0, v39
	v_max_f32_e32 v40, 0, v40
	v_max_f32_e32 v41, 0, v41
	v_cvt_pk_bf16_f32 v20, v20, v21
	v_cvt_pk_bf16_f32 v21, v22, v23
	v_max_f32_e32 v22, v28, v28
	v_max_f32_e32 v23, v29, v29
	v_max_f32_e32 v24, v30, v30
	v_max_f32_e32 v25, v31, v31
	v_add_u32_e32 v11, 0xc000, v11
	v_mul_u32_u24_e32 v12, 0x90, v12
	v_and_b32_e32 v13, 8, v13
	v_pk_mul_f32 v[54:55], v[54:55], v[54:55]
	v_pk_mul_f32 v[56:57], v[56:57], v[56:57]
	v_pk_mul_f32 v[38:39], v[38:39], v[38:39]
	v_pk_mul_f32 v[40:41], v[40:41], v[40:41]
	v_max_f32_e32 v22, 0, v22
	v_max_f32_e32 v23, 0, v23
	v_max_f32_e32 v24, 0, v24
	v_max_f32_e32 v25, 0, v25
	v_add3_u32 v12, v11, v12, v13
	v_cvt_pk_bf16_f32 v54, v54, v55
	v_cvt_pk_bf16_f32 v55, v56, v57
	v_cvt_pk_bf16_f32 v38, v38, v39
	v_cvt_pk_bf16_f32 v39, v40, v41
	v_pk_mul_f32 v[22:23], v[22:23], v[22:23]
	v_pk_mul_f32 v[24:25], v[24:25], v[24:25]
	s_waitcnt vmcnt(0)
; DEVINL void store_rows_via_lds(unsigned char* lds, const u32x2 (&pk)[2][2][4], bf16_t* out_row0, int ld) {
;     ...
;     __syncthreads();
; #pragma unroll
;     for (int mi = 0; mi < 2; ++mi)
; #pragma unroll
;         for (int ni = 0; ni < 2; ++ni)
; #pragma unroll
;             for (int g = 0; g < 4; ++g) *(u32x2*)(reg + (mi * 32 + r) * 144 + (ni * 32 + 8 * g + 4 * h) * 2) = pk[mi][ni][g];
;     __syncthreads();
; #pragma unroll
;     for (int it = 0; it < 8; ++it) {
;         const int idx = it * 64 + lane, row = idx >> 3, c16 = idx & 7;
;         const u32x4 v = *(const u32x4*)(reg + row * 144 + c16 * 16);
;         *(u32x4*)(out_row0 + (size_t)row * ld + c16 * 8) = v;
;     }
	s_nop 0
	ds_write2_b64 v12, v[48:49], v[50:51] offset1:2
	ds_write2_b64 v12, v[52:53], v[54:55] offset0:4 offset1:6
	ds_write2_b64 v12, v[32:33], v[34:35] offset0:8 offset1:10
	ds_write2_b64 v12, v[36:37], v[38:39] offset0:12 offset1:14
	v_add_u32_e32 v12, 0x1000, v12
	v_cvt_pk_bf16_f32 v22, v22, v23
	v_cvt_pk_bf16_f32 v23, v24, v25
	ds_write2_b64 v12, v[16:17], v[18:19] offset0:64 offset1:66
	ds_write2_b64 v12, v[20:21], v[22:23] offset0:68 offset1:70
	ds_write2_b64 v12, v[0:1], v[2:3] offset0:72 offset1:74
	ds_write2_b64 v12, v[4:5], v[6:7] offset0:76 offset1:78
	v_lshlrev_b32_e32 v0, 4, v10
	v_bfe_u32 v6, v10, 3, 3
	v_and_b32_e32 v64, 0x70, v0
	v_mul_u32_u24_e32 v2, 0x90, v6
	v_lshl_add_u64 v[0:1], v[8:9], 0, v[64:65]
	v_add3_u32 v8, v11, v64, v2
	s_waitcnt lgkmcnt(0)
	s_nop 0
	ds_read_b128 v[2:5], v8
	v_lshlrev_b32_e32 v64, 13, v6
	v_lshl_add_u64 v[6:7], v[0:1], 0, v[64:65]
	s_waitcnt lgkmcnt(0)
	global_store_dwordx4 v[6:7], v[2:5], off sc1
	ds_read_b128 v[2:5], v8 offset:1152
	v_or_b32_e32 v6, 0x10000, v64
	v_mov_b32_e32 v7, v65
	v_lshl_add_u64 v[6:7], v[0:1], 0, v[6:7]
	s_waitcnt lgkmcnt(0)
	global_store_dwordx4 v[6:7], v[2:5], off sc1
	ds_read_b128 v[2:5], v8 offset:2304
	v_or_b32_e32 v6, 0x20000, v64
	v_mov_b32_e32 v7, v65
	v_lshl_add_u64 v[6:7], v[0:1], 0, v[6:7]
	s_waitcnt lgkmcnt(0)
	global_store_dwordx4 v[6:7], v[2:5], off sc1
	ds_read_b128 v[2:5], v8 offset:3456
	v_or_b32_e32 v6, 0x30000, v64
	v_mov_b32_e32 v7, v65
	v_lshl_add_u64 v[6:7], v[0:1], 0, v[6:7]
	s_waitcnt lgkmcnt(0)
	global_store_dwordx4 v[6:7], v[2:5], off sc1
	ds_read_b128 v[2:5], v8 offset:4608
	v_or_b32_e32 v6, 0x40000, v64
	v_mov_b32_e32 v7, v65
	v_lshl_add_u64 v[6:7], v[0:1], 0, v[6:7]
	s_waitcnt lgkmcnt(0)
	global_store_dwordx4 v[6:7], v[2:5], off sc1
	ds_read_b128 v[2:5], v8 offset:5760
	v_or_b32_e32 v6, 0x50000, v64
	v_mov_b32_e32 v7, v65
	v_lshl_add_u64 v[6:7], v[0:1], 0, v[6:7]
	s_waitcnt lgkmcnt(0)
	global_store_dwordx4 v[6:7], v[2:5], off sc1
	ds_read_b128 v[2:5], v8 offset:6912
	v_or_b32_e32 v6, 0x60000, v64
	v_mov_b32_e32 v7, v65
	v_lshl_add_u64 v[6:7], v[0:1], 0, v[6:7]
	v_or_b32_e32 v64, 0x70000, v64
	s_waitcnt lgkmcnt(0)
	global_store_dwordx4 v[6:7], v[2:5], off sc1
	ds_read_b128 v[2:5], v8 offset:8064
	v_lshl_add_u64 v[0:1], v[0:1], 0, v[64:65]
	s_waitcnt lgkmcnt(0)
	global_store_dwordx4 v[0:1], v[2:5], off sc1
	s_cbranch_scc0 .LBB0_45

;     DEVINL bf16_t* Z() const { return (bf16_t*)(ws + OFF_Z); }
; #define TID (opq_v((int)threadIdx.x))
; DEVINL unsigned cvt_pk_bf16(float lo, float hi) { const f32x2 v = {lo, hi}; return __builtin_bit_cast(unsigned, __builtin_convertvector(v, bf16x2v)); }
; DEVINL void store_rows_via_lds(unsigned char* lds, const u32x2 (&pk)[2][2][4], bf16_t* out_row0, int ld) {
;     const int tid = TID, lane = tid & 63, w = tid >> 6, r = lane & 31, h = lane >> 5;
;     unsigned char* reg = lds + w * (64 * 144);
;     __syncthreads();
; #pragma unroll
;     for (int mi = 0; mi < 2; ++mi)
; #pragma unroll
;         for (int ni = 0; ni < 2; ++ni)
; #pragma unroll
;             for (int g = 0; g < 4; ++g) *(u32x2*)(reg + (mi * 32 + r) * 144 + (ni * 32 + 8 * g + 4 * h) * 2) = pk[mi][ni][g];
;     __syncthreads();
; #pragma unroll
;     for (int it = 0; it < 8; ++it) {
;         const int idx = it * 64 + lane, row = idx >> 3, c16 = idx & 7;
;         const u32x4 v = *(const u32x4*)(reg + row * 144 + c16 * 16);
;         *(u32x4*)(out_row0 + (size_t)row * ld + c16 * 8) = v;
;     }
; DEVINL void epi_inproj(const Ctx& c, int layer, f32x16 (&acc)[2][2], int mbase, int nbase, unsigned char* lds) {
;     ...
;                 { u32x2 o; o[0] = cvt_pk_bf16(v[0], v[1]); o[1] = cvt_pk_bf16(v[2], v[3]); pkz[mi][ni][g] = o; }
;             }
;     }
;     if (zc >= 0) store_rows_via_lds(lds, pkz, c.Z() + (size_t)mbase * ZW + zc, ZW);
;     if (vt) { const int b0 = mbase / L, p0 = mbase - b0 * L; store_cols_via_lds(lds, pkz, vt + ((size_t)(b0 * vC + vcol)) * L + p0); }
.LBB0_536:
	s_or_b64 exec, exec, s[6:7]
	v_cvt_pk_bf16_f32 v0, v24, v25
	v_cvt_pk_bf16_f32 v1, v26, v27
	v_cvt_pk_bf16_f32 v2, v20, v21
	v_cvt_pk_bf16_f32 v3, v22, v23
	v_cvt_pk_bf16_f32 v4, v16, v17
	v_cvt_pk_bf16_f32 v5, v18, v19
	v_cvt_pk_bf16_f32 v6, v46, v47
	v_cvt_pk_bf16_f32 v7, v90, v91
	v_cvt_pk_bf16_f32 v8, v42, v43
	v_cvt_pk_bf16_f32 v9, v44, v45
	v_cvt_pk_bf16_f32 v10, v38, v39
	v_cvt_pk_bf16_f32 v11, v40, v41
	v_cvt_pk_bf16_f32 v12, v32, v33
	v_cvt_pk_bf16_f32 v13, v34, v35
	v_cvt_pk_bf16_f32 v14, v60, v61
	v_cvt_pk_bf16_f32 v15, v62, v63
	v_cvt_pk_bf16_f32 v18, v56, v57
	v_cvt_pk_bf16_f32 v19, v58, v59
	v_cvt_pk_bf16_f32 v20, v52, v53
	v_cvt_pk_bf16_f32 v21, v54, v55
	v_cvt_pk_bf16_f32 v22, v48, v49
	v_cvt_pk_bf16_f32 v23, v50, v51
	v_cvt_pk_bf16_f32 v24, v86, v87
	v_cvt_pk_bf16_f32 v25, v88, v89
	v_cvt_pk_bf16_f32 v26, v82, v83
	v_cvt_pk_bf16_f32 v27, v84, v85
	v_cvt_pk_bf16_f32 v32, v78, v79
	v_cvt_pk_bf16_f32 v33, v80, v81
	v_cvt_pk_bf16_f32 v34, v74, v75
	v_cvt_pk_bf16_f32 v35, v76, v77
	v_or_b32_e32 v36, s36, v73
	v_cvt_pk_bf16_f32 v16, v28, v29
	v_cvt_pk_bf16_f32 v17, v30, v31
	v_cmp_lt_i32_e32 vcc, -1, v66
	s_and_saveexec_b64 s[6:7], vcc
	s_cbranch_execz .LBB0_538
	v_readlane_b32 s8, v247, 7
	v_readlane_b32 s9, v247, 8
	v_mov_b32_e32 v30, v160
	s_waitcnt vmcnt(0)
	v_mov_b64_e32 v[28:29], s[8:9]
	v_mad_i64_i32 v[28:29], s[8:9], v36, s49, v[28:29]
	v_lshrrev_b32_e32 v31, 6, v30
	s_movk_i32 s8, 0x2400
	v_and_b32_e32 v37, 31, v30
	v_mul_lo_u32 v31, v31, s8
	v_lshrrev_b32_e32 v38, 2, v30
	v_add_u32_e32 v31, 0xc000, v31
	v_mul_u32_u24_e32 v37, 0x90, v37
	v_and_b32_e32 v38, 8, v38
	v_add3_u32 v37, v31, v37, v38
	s_nop 0
	ds_write2_b64 v37, v[34:35], v[32:33] offset1:2
	ds_write2_b64 v37, v[26:27], v[24:25] offset0:4 offset1:6
	ds_write2_b64 v37, v[22:23], v[20:21] offset0:8 offset1:10
	ds_write2_b64 v37, v[18:19], v[14:15] offset0:12 offset1:14
	v_add_u32_e32 v37, 0x1000, v37
	v_mov_b32_e32 v67, v65
	ds_write2_b64 v37, v[12:13], v[10:11] offset0:64 offset1:66
	ds_write2_b64 v37, v[8:9], v[6:7] offset0:68 offset1:70
	ds_write2_b64 v37, v[4:5], v[2:3] offset0:72 offset1:74
	ds_write2_b64 v37, v[0:1], v[16:17] offset0:76 offset1:78
	v_lshlrev_b32_e32 v37, 4, v30
	v_lshl_add_u64 v[28:29], v[66:67], 1, v[28:29]
	v_and_b32_e32 v64, 0x70, v37
	v_bfe_u32 v37, v30, 3, 3
	v_lshl_add_u64 v[42:43], v[28:29], 0, v[64:65]
	v_mul_u32_u24_e32 v28, 0x90, v37
	v_add3_u32 v48, v31, v64, v28
	s_waitcnt lgkmcnt(0)
	s_nop 0
	ds_read_b128 v[28:31], v48
	ds_read_b128 v[38:41], v48 offset:1152
	v_mul_u32_u24_e32 v37, 0x2200, v37
	v_lshlrev_b32_e32 v64, 1, v37
	v_lshl_add_u64 v[44:45], v[42:43], 0, v[64:65]
	s_mov_b32 s8, 0x22000
	s_waitcnt lgkmcnt(1)
	global_store_dwordx4 v[44:45], v[28:31], off sc1
	s_nop 1
	v_add_co_u32_e32 v28, vcc, s8, v44
	s_mov_b32 s8, 0x44000
	s_nop 0
	v_addc_co_u32_e32 v29, vcc, 0, v45, vcc
	s_waitcnt lgkmcnt(0)
	global_store_dwordx4 v[28:29], v[38:41], off sc1
	ds_read_b128 v[28:31], v48 offset:2304
	ds_read_b128 v[38:41], v48 offset:3456
	v_add_co_u32_e32 v46, vcc, s8, v44
	s_mov_b32 s8, 0x66000
	s_nop 0
	v_addc_co_u32_e32 v47, vcc, 0, v45, vcc
	s_waitcnt lgkmcnt(1)
	global_store_dwordx4 v[46:47], v[28:31], off sc1
	s_nop 1
	v_add_co_u32_e32 v28, vcc, s8, v44
	s_mov_b32 s8, 0x88000
	s_nop 0
	v_addc_co_u32_e32 v29, vcc, 0, v45, vcc
	s_waitcnt lgkmcnt(0)
	global_store_dwordx4 v[28:29], v[38:41], off sc1
	ds_read_b128 v[28:31], v48 offset:4608
	ds_read_b128 v[38:41], v48 offset:5760
	v_add_co_u32_e32 v44, vcc, s8, v44
	s_nop 1
	v_addc_co_u32_e32 v45, vcc, 0, v45, vcc
	s_waitcnt lgkmcnt(1)
	global_store_dwordx4 v[44:45], v[28:31], off sc1
	v_add_u32_e32 v44, 0xcc000, v64
	v_mov_b32_e32 v45, v65
	v_add_u32_e32 v28, 0xaa000, v64
	v_mov_b32_e32 v29, v65
	v_lshl_add_u64 v[28:29], v[42:43], 0, v[28:29]
	s_waitcnt lgkmcnt(0)
	global_store_dwordx4 v[28:29], v[38:41], off sc1
	ds_read_b128 v[28:31], v48 offset:6912
	ds_read_b128 v[38:41], v48 offset:8064
	v_lshl_add_u64 v[44:45], v[42:43], 0, v[44:45]
	v_add_u32_e32 v64, 0xee000, v64
	s_waitcnt lgkmcnt(1)
	global_store_dwordx4 v[44:45], v[28:31], off sc1
	s_nop 1
	v_lshl_add_u64 v[28:29], v[42:43], 0, v[64:65]
	s_waitcnt lgkmcnt(0)
	global_store_dwordx4 v[28:29], v[38:41], off sc1
	s_or_b64 exec, exec, s[6:7]
	v_cmp_ne_u64_e32 vcc, 0, v[68:69]
	s_and_saveexec_b64 s[6:7], vcc
	s_cbranch_execz .LBB0_363
	s_branch .LBB0_539

; #define TID (opq_v((int)threadIdx.x))
; DEVINL void store_cols_via_lds(unsigned char* lds, const u32x2 (&pk)[2][2][4], bf16_t* vt_col0  ) {
;     const int tid = TID, lane = tid & 63, w = tid >> 6, r = lane & 31, h = lane >> 5;
;     unsigned char* reg = lds + w * (64 * 144);
;     __syncthreads();
; #pragma unroll
;     for (int mi = 0; mi < 2; ++mi)
; #pragma unroll
;         for (int ni = 0; ni < 2; ++ni)
; #pragma unroll
;             for (int g = 0; g < 4; ++g) {
;                 const int n = ni * 32 + 8 * g + 4 * h, m = mi * 32 + r;
;                 *(bf16_t*)(reg + (n + 0) * 144 + m * 2) = (bf16_t)(pk[mi][ni][g][0] & 0xffffu);
;                 *(bf16_t*)(reg + (n + 1) * 144 + m * 2) = (bf16_t)(pk[mi][ni][g][0] >> 16);
;                 *(bf16_t*)(reg + (n + 2) * 144 + m * 2) = (bf16_t)(pk[mi][ni][g][1] & 0xffffu);
;                 *(bf16_t*)(reg + (n + 3) * 144 + m * 2) = (bf16_t)(pk[mi][ni][g][1] >> 16);
;             }
;     __syncthreads();
; #pragma unroll
;     for (int it = 0; it < 8; ++it) {
;         const int idx = it * 64 + lane, n = idx >> 3, c16 = idx & 7;
;         const u32x4 v = *(const u32x4*)(reg + n * 144 + c16 * 16);
;         *(u32x4*)(vt_col0 + (size_t)n * L + c16 * 8) = v;
;     }
; }
; DEVINL void epi_inproj(const Ctx& c, int layer, f32x16 (&acc)[2][2], int mbase, int nbase, unsigned char* lds) {
;     ...
;     if (vt) { const int b0 = mbase / L, p0 = mbase - b0 * L; store_cols_via_lds(lds, pkz, vt + ((size_t)(b0 * vC + vcol)) * L + p0); }
.LBB0_539:
	s_mov_b32 s8, 0x78787879
	v_mul_hi_i32 v28, v36, s8
	v_lshrrev_b32_e32 v29, 31, v28
	v_ashrrev_i32_e32 v28, 10, v28
	v_add_u32_e32 v29, v28, v29
	s_movk_i32 s8, 0xf780
	v_mad_i32_i24 v28, v29, s8, v36
	v_mad_i32_i24 v29, v94, v29, v93
	s_movk_i32 s8, 0x1100
	v_mad_i64_i32 v[30:31], s[8:9], v29, s8, v[68:69]
	v_ashrrev_i32_e32 v29, 31, v28
	v_lshl_add_u64 v[28:29], v[28:29], 1, v[30:31]
	v_mov_b32_e32 v30, v160
	s_movk_i32 s8, 0x2400
	v_lshrrev_b32_e32 v31, 6, v30
	v_lshrrev_b32_e32 v36, 3, v30
	v_mul_lo_u32 v31, v31, s8
	v_and_b32_e32 v36, 4, v36
	v_lshlrev_b32_e32 v37, 1, v30
	v_add_u32_e32 v31, 0xc000, v31
	v_and_b32_e32 v37, 62, v37
	v_mul_u32_u24_e32 v36, 0x90, v36
	v_add3_u32 v36, v31, v36, v37
	s_waitcnt vmcnt(0)
	s_nop 0
	ds_write_b16 v36, v34
	ds_write_b16_d16_hi v36, v34 offset:144
	ds_write_b16 v36, v35 offset:288
	ds_write_b16_d16_hi v36, v35 offset:432
	ds_write_b16 v36, v32 offset:1152
	ds_write_b16_d16_hi v36, v32 offset:1296
	ds_write_b16 v36, v33 offset:1440
	ds_write_b16_d16_hi v36, v33 offset:1584
	ds_write_b16 v36, v26 offset:2304
	ds_write_b16_d16_hi v36, v26 offset:2448
	ds_write_b16 v36, v27 offset:2592
	ds_write_b16_d16_hi v36, v27 offset:2736
	ds_write_b16 v36, v24 offset:3456
	ds_write_b16_d16_hi v36, v24 offset:3600
	ds_write_b16 v36, v25 offset:3744
	ds_write_b16_d16_hi v36, v25 offset:3888
	ds_write_b16 v36, v22 offset:4608
	ds_write_b16_d16_hi v36, v22 offset:4752
	ds_write_b16 v36, v23 offset:4896
	ds_write_b16_d16_hi v36, v23 offset:5040
	ds_write_b16 v36, v20 offset:5760
	ds_write_b16_d16_hi v36, v20 offset:5904
	ds_write_b16 v36, v21 offset:6048
	ds_write_b16_d16_hi v36, v21 offset:6192
	ds_write_b16 v36, v18 offset:6912
	ds_write_b16_d16_hi v36, v18 offset:7056
	ds_write_b16 v36, v19 offset:7200
	ds_write_b16_d16_hi v36, v19 offset:7344
	ds_write_b16 v36, v14 offset:8064
	ds_write_b16_d16_hi v36, v14 offset:8208
	ds_write_b16 v36, v15 offset:8352
	ds_write_b16_d16_hi v36, v15 offset:8496
	ds_write_b16 v36, v12 offset:64
	ds_write_b16_d16_hi v36, v12 offset:208
	ds_write_b16 v36, v13 offset:352
	ds_write_b16_d16_hi v36, v13 offset:496
	ds_write_b16 v36, v10 offset:1216
	ds_write_b16_d16_hi v36, v10 offset:1360
	ds_write_b16 v36, v11 offset:1504
	ds_write_b16_d16_hi v36, v11 offset:1648
	ds_write_b16 v36, v8 offset:2368
	ds_write_b16_d16_hi v36, v8 offset:2512
	ds_write_b16 v36, v9 offset:2656
	ds_write_b16_d16_hi v36, v9 offset:2800
	ds_write_b16 v36, v6 offset:3520
	ds_write_b16_d16_hi v36, v6 offset:3664
	ds_write_b16 v36, v7 offset:3808
	ds_write_b16_d16_hi v36, v7 offset:3952
	ds_write_b16 v36, v4 offset:4672
	ds_write_b16_d16_hi v36, v4 offset:4816
	ds_write_b16 v36, v5 offset:4960
	ds_write_b16_d16_hi v36, v5 offset:5104
	ds_write_b16 v36, v2 offset:5824
	ds_write_b16_d16_hi v36, v2 offset:5968
	ds_write_b16 v36, v3 offset:6112
	ds_write_b16_d16_hi v36, v3 offset:6256
	ds_write_b16 v36, v0 offset:6976
	ds_write_b16_d16_hi v36, v0 offset:7120
	ds_write_b16 v36, v1 offset:7264
	ds_write_b16_d16_hi v36, v1 offset:7408
	ds_write_b16 v36, v16 offset:8128
	ds_write_b16_d16_hi v36, v16 offset:8272
	ds_write_b16 v36, v17 offset:8416
	ds_write_b16_d16_hi v36, v17 offset:8560
	v_lshlrev_b32_e32 v0, 4, v30
	v_bfe_u32 v4, v30, 3, 3
	v_and_b32_e32 v64, 0x70, v0
	v_mul_u32_u24_e32 v0, 0x90, v4
	v_add3_u32 v14, v31, v64, v0
	s_waitcnt lgkmcnt(0)
	s_nop 0
	ds_read_b128 v[0:3], v14
	v_mul_u32_u24_e32 v4, 0x880, v4
	v_lshl_add_u64 v[8:9], v[28:29], 0, v[64:65]
	v_lshlrev_b32_e32 v64, 1, v4
	ds_read_b128 v[4:7], v14 offset:1152
	v_lshl_add_u64 v[10:11], v[8:9], 0, v[64:65]
	s_mov_b32 s8, 0x8000
	s_waitcnt lgkmcnt(1)
	global_store_dwordx4 v[10:11], v[0:3], off sc1
	s_nop 1
	v_add_co_u32_e32 v0, vcc, s8, v10
	s_mov_b32 s8, 0x11000
	s_nop 0
	v_addc_co_u32_e32 v1, vcc, 0, v11, vcc
	s_waitcnt lgkmcnt(0)
	global_store_dwordx4 v[0:1], v[4:7], off offset:2048 sc1
	ds_read_b128 v[0:3], v14 offset:2304
	ds_read_b128 v[4:7], v14 offset:3456
	v_add_co_u32_e32 v12, vcc, s8, v10
	s_mov_b32 s8, 0x19000
	s_nop 0
	v_addc_co_u32_e32 v13, vcc, 0, v11, vcc
	s_waitcnt lgkmcnt(1)
	global_store_dwordx4 v[12:13], v[0:3], off sc1
	s_nop 1
	v_add_co_u32_e32 v0, vcc, s8, v10
	s_mov_b32 s8, 0x22000
	s_nop 0
	v_addc_co_u32_e32 v1, vcc, 0, v11, vcc
	s_waitcnt lgkmcnt(0)
	global_store_dwordx4 v[0:1], v[4:7], off offset:2048 sc1
	ds_read_b128 v[0:3], v14 offset:4608
	ds_read_b128 v[4:7], v14 offset:5760
	v_add_co_u32_e32 v10, vcc, s8, v10
	s_nop 1
	v_addc_co_u32_e32 v11, vcc, 0, v11, vcc
	s_waitcnt lgkmcnt(1)
	global_store_dwordx4 v[10:11], v[0:3], off sc1
	v_add_u32_e32 v10, 0x33000, v64
	v_mov_b32_e32 v11, v65
	v_add_u32_e32 v0, 0x2a800, v64
	v_mov_b32_e32 v1, v65
	v_lshl_add_u64 v[0:1], v[8:9], 0, v[0:1]
	s_waitcnt lgkmcnt(0)
	global_store_dwordx4 v[0:1], v[4:7], off sc1
	ds_read_b128 v[0:3], v14 offset:6912
	ds_read_b128 v[4:7], v14 offset:8064
	v_lshl_add_u64 v[10:11], v[8:9], 0, v[10:11]
	v_add_u32_e32 v64, 0x3b800, v64
	s_waitcnt lgkmcnt(1)
	global_store_dwordx4 v[10:11], v[0:3], off sc1
	s_nop 1
	v_lshl_add_u64 v[0:1], v[8:9], 0, v[64:65]
	s_waitcnt lgkmcnt(0)
	global_store_dwordx4 v[0:1], v[4:7], off sc1
	s_branch .LBB0_363
